# K-loops: no VALU in load segments - LDS-DMA in saddr form with scalar bases, B-fragment LDS reads from one hoisted base VGPR
# speedup vs baseline: 1.0005x; 1.0005x over previous
; #define PG8_STAGEA(bufoff, gbase, voff) PG8_STAGE_X(bufoff, gbase, voff, AUXA)
; #define PG8_LDA(dst, b, h) do { _Pragma("unroll") for (int m = 0; m < 4; ++m) _Pragma("unroll") for (int k = 0; k < 2; ++k) dst[m][k] = *(const PG8_LAS bf16x8*)(lds + PG8_SA(b, h) + aoff + m * 2048 + k * 1024); } while (0)
; #define PG8_LDB(dst, b, h) do { _Pragma("unroll") for (int n = 0; n < 2; ++n) _Pragma("unroll") for (int k = 0; k < 2; ++k) dst[n][k] = *(const PG8_LAS bf16x8*)(lds + PG8_SB(b, h) + boff + n * 2048 + k * 1024); } while (0)
; #define PG8_MMA(ai, bj, At, Bt) do { if (GEMM_PRIO_MODE == 0) __builtin_amdgcn_s_setprio(1); PG8_MMA_LOOPS \
;         acc[ai][bj][m][n] = __builtin_amdgcn_mfma_f32_16x16x32_bf16(Bt[n][k], At[m][k], acc[ai][bj][m][n], 0, 0, 0); if (GEMM_PRIO_MODE == 0) __builtin_amdgcn_s_setprio(0); } while (0)
; #define PG8_WAIT_V(n) asm volatile("s_waitcnt vmcnt(" #n ")" ::: "memory")
; #define PG8_WAIT_VR(n, nr, flag) asm volatile("s_cmp_eq_u32 %0, 0\n\ts_cbranch_scc1 .Lpg8s%=\n\ts_waitcnt vmcnt(" #nr ")\n\ts_branch .Lpg8d%=\n.Lpg8s%=:\n\ts_waitcnt vmcnt(" #n ")\n.Lpg8d%=:" :: "s"(flag) : "memory", "scc")
;     ...
;         for (int t = t0; t < nt; t += 2) {
;             const bool last = (t == nt - 2);
;             const char* a1 = cA + (size_t)(t + 1) * kstepA;
;             const char* a2 = last ? nA : cA + (size_t)(t + 2) * kstepA; const char* b2 = last ? nB : cB + (size_t)(t + 2) * kstepB;
;             const char* a3 = a2 + kstepA; const char* b3 = b2 + kstepB;
;             if (last && has_next) S.a_ready(nxt);
;             if constexpr (SP2) {
;             PG8_LDB(B0, 0, 0); PG8_LDB(B1, 0, 1); PG8_SCHED; PG8_LDA(At, 0, 0); PG8_STAGEA(PG8_SA(1, 1), a1 + hstepA, voffA);
;     ...
;             const int relax = __builtin_amdgcn_readfirstlane((t == 0 && ui > 0) ? 1 : 0);
;             PG8_WAIT_VR(8, 24, relax); PG8_WAIT_L(0); PG8_BAR; PG8_MMA(0, 0, At, B0); PG8_MMA(0, 1, At, B1); PG8_BAR; PG8_SCHED;
;     ...
;             PG8_WAIT_V(8); PG8_WAIT_L(0); PG8_BAR; PG8_MMA(0, 0, At, B0); PG8_MMA(0, 1, At, B1); PG8_BAR; PG8_SCHED;
;     ...
; #pragma unroll
;         for (int a = 0; a < 2; ++a)
; #pragma unroll
;             for (int b = 0; b < 2; ++b)
; #pragma unroll
;                 for (int m = 0; m < 4; ++m)
; #pragma unroll
;                     for (int n = 0; n < 2; ++n) acc[a][b][m][n] = (f32x4){0.f, 0.f, 0.f, 0.f};
;         cur = nxt; cA = nA; cB = nB; ++ui;
.LBB0_128:
	s_ashr_i32 s37, s36, 31
	s_lshl_b64 s[4:5], s[36:37], 21
	s_add_u32 s38, s56, s4
	s_addc_u32 s39, s57, s5
	s_and_b64 s[4:5], s[6:7], exec
	s_cselect_b32 s4, s39, s1
	s_cselect_b32 s5, s38, s0
	s_ashr_i32 s27, s26, 31
	s_lshl_b64 s[8:9], s[26:27], 21
	s_add_u32 s40, s43, s8
	s_addc_u32 s41, s50, s9
	s_and_b64 s[8:9], s[6:7], exec
	s_cselect_b32 s16, s41, s11
	s_cselect_b32 s17, s40, s10
	s_add_u32 s8, s0, 0x100080
	s_addc_u32 s9, s1, 0
	s_add_u32 s0, s10, 0x100
	v_mov_b32_e32 v0, 0
	s_addc_u32 s1, s11, 0
	s_mov_b32 s27, -2
	v_mov_b32_e32 v1, v0
	v_mov_b32_e32 v2, v0
	v_mov_b32_e32 v3, v0
	v_mov_b32_e32 v4, v0
	v_mov_b32_e32 v5, v0
	v_mov_b32_e32 v6, v0
	v_mov_b32_e32 v7, v0
	v_mov_b32_e32 v18, v0
	v_mov_b32_e32 v19, v0
	v_mov_b32_e32 v20, v0
	v_mov_b32_e32 v21, v0
	v_mov_b32_e32 v22, v0
	v_mov_b32_e32 v23, v0
	v_mov_b32_e32 v24, v0
	v_mov_b32_e32 v25, v0
	v_mov_b32_e32 v34, v0
	v_mov_b32_e32 v35, v0
	v_mov_b32_e32 v36, v0
	v_mov_b32_e32 v37, v0
	v_mov_b32_e32 v38, v0
	v_mov_b32_e32 v39, v0
	v_mov_b32_e32 v40, v0
	v_mov_b32_e32 v41, v0
	v_mov_b32_e32 v50, v0
	v_mov_b32_e32 v51, v0
	v_mov_b32_e32 v52, v0
	v_mov_b32_e32 v53, v0
	v_mov_b32_e32 v54, v0
	v_mov_b32_e32 v55, v0
	v_mov_b32_e32 v56, v0
	v_mov_b32_e32 v57, v0
	v_mov_b32_e32 v8, v0
	v_mov_b32_e32 v9, v0
	v_mov_b32_e32 v10, v0
	v_mov_b32_e32 v11, v0
	v_mov_b32_e32 v12, v0
	v_mov_b32_e32 v13, v0
	v_mov_b32_e32 v14, v0
	v_mov_b32_e32 v15, v0
	v_mov_b32_e32 v26, v0
	v_mov_b32_e32 v27, v0
	v_mov_b32_e32 v28, v0
	v_mov_b32_e32 v29, v0
	v_mov_b32_e32 v30, v0
	v_mov_b32_e32 v31, v0
	v_mov_b32_e32 v32, v0
	v_mov_b32_e32 v33, v0
	v_mov_b32_e32 v42, v0
	v_mov_b32_e32 v43, v0
	v_mov_b32_e32 v44, v0
	v_mov_b32_e32 v45, v0
	v_mov_b32_e32 v46, v0
	v_mov_b32_e32 v47, v0
	v_mov_b32_e32 v48, v0
	v_mov_b32_e32 v49, v0
	v_mov_b32_e32 v58, v0
	v_mov_b32_e32 v59, v0
	v_mov_b32_e32 v60, v0
	v_mov_b32_e32 v61, v0
	v_mov_b32_e32 v62, v0
	v_mov_b32_e32 v63, v0
	v_mov_b32_e32 v64, v0
	v_mov_b32_e32 v65, v0
	v_mov_b32_e32 v66, v0
	v_mov_b32_e32 v67, v0
	v_mov_b32_e32 v68, v0
	v_mov_b32_e32 v69, v0
	v_mov_b32_e32 v70, v0
	v_mov_b32_e32 v71, v0
	v_mov_b32_e32 v72, v0
	v_mov_b32_e32 v73, v0
	v_mov_b32_e32 v82, v0
	v_mov_b32_e32 v83, v0
	v_mov_b32_e32 v84, v0
	v_mov_b32_e32 v85, v0
	v_mov_b32_e32 v86, v0
	v_mov_b32_e32 v87, v0
	v_mov_b32_e32 v88, v0
	v_mov_b32_e32 v89, v0
	v_mov_b32_e32 v98, v0
	v_mov_b32_e32 v99, v0
	v_mov_b32_e32 v100, v0
	v_mov_b32_e32 v101, v0
	v_mov_b32_e32 v102, v0
	v_mov_b32_e32 v103, v0
	v_mov_b32_e32 v104, v0
	v_mov_b32_e32 v105, v0
	v_mov_b32_e32 v114, v0
	v_mov_b32_e32 v115, v0
	v_mov_b32_e32 v116, v0
	v_mov_b32_e32 v117, v0
	v_mov_b32_e32 v118, v0
	v_mov_b32_e32 v119, v0
	v_mov_b32_e32 v120, v0
	v_mov_b32_e32 v121, v0
	v_mov_b32_e32 v74, v0
	v_mov_b32_e32 v75, v0
	v_mov_b32_e32 v76, v0
	v_mov_b32_e32 v77, v0
	v_mov_b32_e32 v78, v0
	v_mov_b32_e32 v79, v0
	v_mov_b32_e32 v80, v0
	v_mov_b32_e32 v81, v0
	v_mov_b32_e32 v90, v0
	v_mov_b32_e32 v91, v0
	v_mov_b32_e32 v92, v0
	v_mov_b32_e32 v93, v0
	v_mov_b32_e32 v94, v0
	v_mov_b32_e32 v95, v0
	v_mov_b32_e32 v96, v0
	v_mov_b32_e32 v97, v0
	v_mov_b32_e32 v106, v0
	v_mov_b32_e32 v107, v0
	v_mov_b32_e32 v108, v0
	v_mov_b32_e32 v109, v0
	v_mov_b32_e32 v110, v0
	v_mov_b32_e32 v111, v0
	v_mov_b32_e32 v112, v0
	v_mov_b32_e32 v113, v0
	v_mov_b32_e32 v122, v0
	v_mov_b32_e32 v123, v0
	v_mov_b32_e32 v124, v0
	v_mov_b32_e32 v125, v0
	v_mov_b32_e32 v126, v0
	v_mov_b32_e32 v127, v0
	v_mov_b32_e32 v128, v0
	v_mov_b32_e32 v129, v0
	v_add_u32_e32 v226, 0x10000, v167
.LBB0_129:
	s_add_u32 s10, s8, 0xfff00080
	s_addc_u32 s11, s9, -1
	s_add_i32 s18, 0, 0x10000
	s_cmp_eq_u32 s27, 60
	s_cselect_b32 s15, s4, s11
	s_cselect_b32 s14, s5, s10
	s_cselect_b32 s11, s16, s1
	s_cselect_b32 s10, s17, s0
	s_add_i32 s20, 0, 0x14000
	s_waitcnt lgkmcnt(0)
	ds_read_b128 v[130:133], v226
	ds_read_b128 v[134:137], v226 offset:1024
	ds_read_b128 v[152:155], v226 offset:2048
	ds_read_b128 v[156:159], v226 offset:3072
	ds_read_b128 v[160:163], v226 offset:16384
	ds_read_b128 v[174:177], v226 offset:17408
	ds_read_b128 v[178:181], v226 offset:18432
	ds_read_b128 v[182:185], v226 offset:19456
	s_add_i32 m0, s51, 0xc000
	ds_read_b128 v[186:189], v172
	ds_read_b128 v[190:193], v172 offset:1024
	ds_read_b128 v[194:197], v172 offset:2048
	ds_read_b128 v[198:201], v172 offset:3072
	ds_read_b128 v[202:205], v172 offset:4096
	ds_read_b128 v[206:209], v172 offset:5120
	ds_read_b128 v[210:213], v172 offset:6144
	ds_read_b128 v[214:217], v172 offset:7168
	global_load_lds_dwordx4 v148, s[8:9]
	s_add_i32 m0, s51, 0xe000
	s_nop 0
	global_load_lds_dwordx4 v150, s[8:9]
	s_waitcnt vmcnt(8)
	s_waitcnt lgkmcnt(0)
	s_setprio 1
	s_barrier
; #define PG8_STAGEA(bufoff, gbase, voff) PG8_STAGE_X(bufoff, gbase, voff, AUXA)
; #define PG8_STAGEB(bufoff, gbase, voff) PG8_STAGE_X(bufoff, gbase, voff, AUXB)
; #define PG8_LDA(dst, b, h) do { _Pragma("unroll") for (int m = 0; m < 4; ++m) _Pragma("unroll") for (int k = 0; k < 2; ++k) dst[m][k] = *(const PG8_LAS bf16x8*)(lds + PG8_SA(b, h) + aoff + m * 2048 + k * 1024); } while (0)
; #define PG8_MMA(ai, bj, At, Bt) do { if (GEMM_PRIO_MODE == 0) __builtin_amdgcn_s_setprio(1); PG8_MMA_LOOPS \
;         acc[ai][bj][m][n] = __builtin_amdgcn_mfma_f32_16x16x32_bf16(Bt[n][k], At[m][k], acc[ai][bj][m][n], 0, 0, 0); if (GEMM_PRIO_MODE == 0) __builtin_amdgcn_s_setprio(0); } while (0)
; #define PG8_WAIT_V(n) asm volatile("s_waitcnt vmcnt(" #n ")" ::: "memory")
; #define PG8_WAIT_VR(n, nr, flag) asm volatile("s_cmp_eq_u32 %0, 0\n\ts_cbranch_scc1 .Lpg8s%=\n\ts_waitcnt vmcnt(" #nr ")\n\ts_branch .Lpg8d%=\n.Lpg8s%=:\n\ts_waitcnt vmcnt(" #n ")\n.Lpg8d%=:" :: "s"(flag) : "memory", "scc")
; #define PG8_WAIT_L(n) asm volatile("s_waitcnt lgkmcnt(" #n ")" ::: "memory")
; #define PG8_BAR __builtin_amdgcn_s_barrier()
; #define PG8_SCHED __builtin_amdgcn_sched_barrier(0)
;     ...
;             PG8_WAIT_V(8); PG8_WAIT_L(0); PG8_BAR; PG8_MMA(0, 0, At, B0); PG8_MMA(0, 1, At, B1); PG8_BAR; PG8_SCHED;
;     ...
;             PG8_LDA(At, 0, 1); PG8_STAGEB(PG8_SB(0, 0), b2, voffB); PG8_STAGEB(PG8_SB(0, 1), b2 + hstepB, voffB); PG8_STAGEA(PG8_SA(0, 0), a2, voffA);
;     ...
;             PG8_WAIT_VR(8, 24, relax); PG8_WAIT_L(0); PG8_BAR; PG8_MMA(1, 0, At, B0); PG8_MMA(1, 1, At, B1); PG8_BAR; PG8_SCHED;
;     ...
;             PG8_WAIT_V(8); PG8_WAIT_L(0); PG8_BAR; PG8_MMA(1, 0, At, B0); PG8_MMA(1, 1, At, B1); PG8_BAR; PG8_SCHED;
	v_mfma_f32_16x16x32_bf16 v[126:129], v[130:133], v[186:189], v[126:129]
	v_mfma_f32_16x16x32_bf16 v[122:125], v[152:155], v[186:189], v[122:125]
	v_mfma_f32_16x16x32_bf16 v[110:113], v[130:133], v[194:197], v[110:113]
	v_mfma_f32_16x16x32_bf16 v[106:109], v[152:155], v[194:197], v[106:109]
	v_mfma_f32_16x16x32_bf16 v[94:97], v[130:133], v[202:205], v[94:97]
	v_mfma_f32_16x16x32_bf16 v[90:93], v[152:155], v[202:205], v[90:93]
	v_mfma_f32_16x16x32_bf16 v[78:81], v[130:133], v[210:213], v[78:81]
	v_mfma_f32_16x16x32_bf16 v[74:77], v[152:155], v[210:213], v[74:77]
	v_mfma_f32_16x16x32_bf16 v[126:129], v[134:137], v[190:193], v[126:129]
	v_mfma_f32_16x16x32_bf16 v[122:125], v[156:159], v[190:193], v[122:125]
	v_mfma_f32_16x16x32_bf16 v[110:113], v[134:137], v[198:201], v[110:113]
	v_mfma_f32_16x16x32_bf16 v[106:109], v[156:159], v[198:201], v[106:109]
	v_mfma_f32_16x16x32_bf16 v[94:97], v[134:137], v[206:209], v[94:97]
	v_mfma_f32_16x16x32_bf16 v[90:93], v[156:159], v[206:209], v[90:93]
	v_mfma_f32_16x16x32_bf16 v[78:81], v[134:137], v[214:217], v[78:81]
	v_mfma_f32_16x16x32_bf16 v[74:77], v[156:159], v[214:217], v[74:77]
	v_mfma_f32_16x16x32_bf16 v[118:121], v[160:163], v[186:189], v[118:121]
	v_mfma_f32_16x16x32_bf16 v[114:117], v[178:181], v[186:189], v[114:117]
	v_mfma_f32_16x16x32_bf16 v[102:105], v[160:163], v[194:197], v[102:105]
	v_mfma_f32_16x16x32_bf16 v[98:101], v[178:181], v[194:197], v[98:101]
	v_mfma_f32_16x16x32_bf16 v[86:89], v[160:163], v[202:205], v[86:89]
	v_mfma_f32_16x16x32_bf16 v[82:85], v[178:181], v[202:205], v[82:85]
	v_mfma_f32_16x16x32_bf16 v[70:73], v[160:163], v[210:213], v[70:73]
	v_mfma_f32_16x16x32_bf16 v[66:69], v[178:181], v[210:213], v[66:69]
	v_mfma_f32_16x16x32_bf16 v[118:121], v[174:177], v[190:193], v[118:121]
	v_mfma_f32_16x16x32_bf16 v[114:117], v[182:185], v[190:193], v[114:117]
	v_mfma_f32_16x16x32_bf16 v[102:105], v[174:177], v[198:201], v[102:105]
	v_mfma_f32_16x16x32_bf16 v[98:101], v[182:185], v[198:201], v[98:101]
	v_mfma_f32_16x16x32_bf16 v[86:89], v[174:177], v[206:209], v[86:89]
	v_mfma_f32_16x16x32_bf16 v[82:85], v[182:185], v[206:209], v[82:85]
	v_mfma_f32_16x16x32_bf16 v[70:73], v[174:177], v[214:217], v[70:73]
	v_mfma_f32_16x16x32_bf16 v[66:69], v[182:185], v[214:217], v[66:69]
	s_barrier
	s_setprio 0
	s_add_i32 s18, s18, s42
	s_mov_b32 m0, s18
	ds_read_b128 v[186:189], v172 offset:16384
	ds_read_b128 v[190:193], v172 offset:17408
	ds_read_b128 v[194:197], v172 offset:18432
	ds_read_b128 v[198:201], v172 offset:19456
	ds_read_b128 v[202:205], v172 offset:20480
	ds_read_b128 v[206:209], v172 offset:21504
	ds_read_b128 v[210:213], v172 offset:22528
	ds_read_b128 v[214:217], v172 offset:23552
	s_add_u32 s100, s14, 0x80
	s_addc_u32 s101, s15, 0
	global_load_lds_dwordx4 v142, s[10:11]
	s_add_i32 m0, s18, 0x2000
	s_add_u32 s18, s10, 0x100000
	s_addc_u32 s19, s11, 0
	s_add_i32 s20, s20, s42
	global_load_lds_dwordx4 v138, s[10:11]
	s_mov_b32 m0, s20
	s_nop 0
	global_load_lds_dwordx4 v142, s[18:19]
	s_add_i32 m0, s20, 0x2000
	s_nop 0
	global_load_lds_dwordx4 v138, s[18:19]
	s_mov_b32 m0, s51
	s_nop 0
	global_load_lds_dwordx4 v144, s[14:15]
	s_mov_b32 m0, s68
	s_nop 0
	global_load_lds_dwordx4 v140, s[14:15]
	s_waitcnt vmcnt(8)
	s_waitcnt lgkmcnt(0)
	s_setprio 1
	s_barrier
	v_mfma_f32_16x16x32_bf16 v[62:65], v[130:133], v[186:189], v[62:65]
	v_mfma_f32_16x16x32_bf16 v[58:61], v[152:155], v[186:189], v[58:61]
	v_mfma_f32_16x16x32_bf16 v[46:49], v[130:133], v[194:197], v[46:49]
	v_mfma_f32_16x16x32_bf16 v[42:45], v[152:155], v[194:197], v[42:45]
	v_mfma_f32_16x16x32_bf16 v[30:33], v[130:133], v[202:205], v[30:33]
	v_mfma_f32_16x16x32_bf16 v[26:29], v[152:155], v[202:205], v[26:29]
	v_mfma_f32_16x16x32_bf16 v[12:15], v[130:133], v[210:213], v[12:15]
	v_mfma_f32_16x16x32_bf16 v[8:11], v[152:155], v[210:213], v[8:11]
	v_mfma_f32_16x16x32_bf16 v[62:65], v[134:137], v[190:193], v[62:65]
	v_mfma_f32_16x16x32_bf16 v[58:61], v[156:159], v[190:193], v[58:61]
	v_mfma_f32_16x16x32_bf16 v[46:49], v[134:137], v[198:201], v[46:49]
	v_mfma_f32_16x16x32_bf16 v[42:45], v[156:159], v[198:201], v[42:45]
	v_mfma_f32_16x16x32_bf16 v[30:33], v[134:137], v[206:209], v[30:33]
	v_mfma_f32_16x16x32_bf16 v[26:29], v[156:159], v[206:209], v[26:29]
	v_mfma_f32_16x16x32_bf16 v[12:15], v[134:137], v[214:217], v[12:15]
	v_mfma_f32_16x16x32_bf16 v[8:11], v[156:159], v[214:217], v[8:11]
	v_mfma_f32_16x16x32_bf16 v[54:57], v[160:163], v[186:189], v[54:57]
	v_mfma_f32_16x16x32_bf16 v[50:53], v[178:181], v[186:189], v[50:53]
	v_mfma_f32_16x16x32_bf16 v[38:41], v[160:163], v[194:197], v[38:41]
	v_mfma_f32_16x16x32_bf16 v[34:37], v[178:181], v[194:197], v[34:37]
	v_mfma_f32_16x16x32_bf16 v[22:25], v[160:163], v[202:205], v[22:25]
	v_mfma_f32_16x16x32_bf16 v[18:21], v[178:181], v[202:205], v[18:21]
	v_mfma_f32_16x16x32_bf16 v[4:7], v[160:163], v[210:213], v[4:7]
	v_mfma_f32_16x16x32_bf16 v[0:3], v[178:181], v[210:213], v[0:3]
	v_mfma_f32_16x16x32_bf16 v[54:57], v[174:177], v[190:193], v[54:57]
	v_mfma_f32_16x16x32_bf16 v[50:53], v[182:185], v[190:193], v[50:53]
	v_mfma_f32_16x16x32_bf16 v[38:41], v[174:177], v[198:201], v[38:41]
	v_mfma_f32_16x16x32_bf16 v[34:37], v[182:185], v[198:201], v[34:37]
	v_mfma_f32_16x16x32_bf16 v[22:25], v[174:177], v[206:209], v[22:25]
	v_mfma_f32_16x16x32_bf16 v[18:21], v[182:185], v[206:209], v[18:21]
	v_mfma_f32_16x16x32_bf16 v[4:7], v[174:177], v[214:217], v[4:7]
	v_mfma_f32_16x16x32_bf16 v[0:3], v[182:185], v[214:217], v[0:3]
	s_barrier
; #define PG8_STAGEA(bufoff, gbase, voff) PG8_STAGE_X(bufoff, gbase, voff, AUXA)
; #define PG8_STAGEB(bufoff, gbase, voff) PG8_STAGE_X(bufoff, gbase, voff, AUXB)
; #define PG8_LDA(dst, b, h) do { _Pragma("unroll") for (int m = 0; m < 4; ++m) _Pragma("unroll") for (int k = 0; k < 2; ++k) dst[m][k] = *(const PG8_LAS bf16x8*)(lds + PG8_SA(b, h) + aoff + m * 2048 + k * 1024); } while (0)
; #define PG8_LDB(dst, b, h) do { _Pragma("unroll") for (int n = 0; n < 2; ++n) _Pragma("unroll") for (int k = 0; k < 2; ++k) dst[n][k] = *(const PG8_LAS bf16x8*)(lds + PG8_SB(b, h) + boff + n * 2048 + k * 1024); } while (0)
; #define PG8_MMA(ai, bj, At, Bt) do { if (GEMM_PRIO_MODE == 0) __builtin_amdgcn_s_setprio(1); PG8_MMA_LOOPS \
;         acc[ai][bj][m][n] = __builtin_amdgcn_mfma_f32_16x16x32_bf16(Bt[n][k], At[m][k], acc[ai][bj][m][n], 0, 0, 0); if (GEMM_PRIO_MODE == 0) __builtin_amdgcn_s_setprio(0); } while (0)
; #define PG8_WAIT_V(n) asm volatile("s_waitcnt vmcnt(" #n ")" ::: "memory")
; #define PG8_WAIT_L(n) asm volatile("s_waitcnt lgkmcnt(" #n ")" ::: "memory")
; #define PG8_BAR __builtin_amdgcn_s_barrier()
; #define PG8_SCHED __builtin_amdgcn_sched_barrier(0)
;     ...
;             PG8_LDB(B0, 1, 0); PG8_LDB(B1, 1, 1); PG8_SCHED; PG8_LDA(At, 1, 0); PG8_STAGEA(PG8_SA(0, 1), a2 + hstepA, voffA);
;             PG8_WAIT_V(8); PG8_WAIT_L(0); PG8_BAR; PG8_MMA(0, 0, At, B0); PG8_MMA(0, 1, At, B1); PG8_BAR; PG8_SCHED;
;             PG8_LDA(At, 1, 1); PG8_STAGEB(PG8_SB(1, 0), b3, voffB); PG8_STAGEB(PG8_SB(1, 1), b3 + hstepB, voffB); PG8_STAGEA(PG8_SA(1, 0), a3, voffA);
;             PG8_WAIT_V(8); PG8_WAIT_L(0); PG8_BAR; PG8_MMA(1, 0, At, B0); PG8_MMA(1, 1, At, B1); PG8_BAR; PG8_SCHED;
	s_setprio 0
	s_add_i32 s18, 0, 0x18000
	s_add_i32 s19, 0, 0x1c000
	ds_read_b128 v[130:133], v226 offset:32768
	ds_read_b128 v[134:137], v226 offset:33792
	ds_read_b128 v[152:155], v226 offset:34816
	ds_read_b128 v[156:159], v226 offset:35840
	ds_read_b128 v[160:163], v226 offset:49152
	ds_read_b128 v[174:177], v226 offset:50176
	ds_read_b128 v[178:181], v226 offset:51200
	ds_read_b128 v[182:185], v226 offset:52224
	s_add_u32 s14, s14, 0x100000
	s_addc_u32 s15, s15, 0
	s_mov_b32 m0, s69
	ds_read_b128 v[186:189], v172 offset:32768
	ds_read_b128 v[190:193], v172 offset:33792
	ds_read_b128 v[194:197], v172 offset:34816
	ds_read_b128 v[198:201], v172 offset:35840
	ds_read_b128 v[202:205], v172 offset:36864
	ds_read_b128 v[206:209], v172 offset:37888
	ds_read_b128 v[210:213], v172 offset:38912
	ds_read_b128 v[214:217], v172 offset:39936
	global_load_lds_dwordx4 v144, s[14:15]
	s_mov_b32 m0, s72
	s_nop 0
	global_load_lds_dwordx4 v140, s[14:15]
	s_waitcnt vmcnt(8)
	s_waitcnt lgkmcnt(0)
	s_setprio 1
	s_barrier
	v_mfma_f32_16x16x32_bf16 v[126:129], v[130:133], v[186:189], v[126:129]
	v_mfma_f32_16x16x32_bf16 v[122:125], v[152:155], v[186:189], v[122:125]
	v_mfma_f32_16x16x32_bf16 v[110:113], v[130:133], v[194:197], v[110:113]
	v_mfma_f32_16x16x32_bf16 v[106:109], v[152:155], v[194:197], v[106:109]
	v_mfma_f32_16x16x32_bf16 v[94:97], v[130:133], v[202:205], v[94:97]
	v_mfma_f32_16x16x32_bf16 v[90:93], v[152:155], v[202:205], v[90:93]
	v_mfma_f32_16x16x32_bf16 v[78:81], v[130:133], v[210:213], v[78:81]
	v_mfma_f32_16x16x32_bf16 v[74:77], v[152:155], v[210:213], v[74:77]
	v_mfma_f32_16x16x32_bf16 v[126:129], v[134:137], v[190:193], v[126:129]
	v_mfma_f32_16x16x32_bf16 v[122:125], v[156:159], v[190:193], v[122:125]
	v_mfma_f32_16x16x32_bf16 v[110:113], v[134:137], v[198:201], v[110:113]
	v_mfma_f32_16x16x32_bf16 v[106:109], v[156:159], v[198:201], v[106:109]
	v_mfma_f32_16x16x32_bf16 v[94:97], v[134:137], v[206:209], v[94:97]
	v_mfma_f32_16x16x32_bf16 v[90:93], v[156:159], v[206:209], v[90:93]
	v_mfma_f32_16x16x32_bf16 v[78:81], v[134:137], v[214:217], v[78:81]
	v_mfma_f32_16x16x32_bf16 v[74:77], v[156:159], v[214:217], v[74:77]
	v_mfma_f32_16x16x32_bf16 v[118:121], v[160:163], v[186:189], v[118:121]
	v_mfma_f32_16x16x32_bf16 v[114:117], v[178:181], v[186:189], v[114:117]
	v_mfma_f32_16x16x32_bf16 v[102:105], v[160:163], v[194:197], v[102:105]
	v_mfma_f32_16x16x32_bf16 v[98:101], v[178:181], v[194:197], v[98:101]
	v_mfma_f32_16x16x32_bf16 v[86:89], v[160:163], v[202:205], v[86:89]
	v_mfma_f32_16x16x32_bf16 v[82:85], v[178:181], v[202:205], v[82:85]
	v_mfma_f32_16x16x32_bf16 v[70:73], v[160:163], v[210:213], v[70:73]
	v_mfma_f32_16x16x32_bf16 v[66:69], v[178:181], v[210:213], v[66:69]
	v_mfma_f32_16x16x32_bf16 v[118:121], v[174:177], v[190:193], v[118:121]
	v_mfma_f32_16x16x32_bf16 v[114:117], v[182:185], v[190:193], v[114:117]
	v_mfma_f32_16x16x32_bf16 v[102:105], v[174:177], v[198:201], v[102:105]
	v_mfma_f32_16x16x32_bf16 v[98:101], v[182:185], v[198:201], v[98:101]
	v_mfma_f32_16x16x32_bf16 v[86:89], v[174:177], v[206:209], v[86:89]
	v_mfma_f32_16x16x32_bf16 v[82:85], v[182:185], v[206:209], v[82:85]
	v_mfma_f32_16x16x32_bf16 v[70:73], v[174:177], v[214:217], v[70:73]
	v_mfma_f32_16x16x32_bf16 v[66:69], v[182:185], v[214:217], v[66:69]
	s_barrier
	s_setprio 0
	s_add_i32 s14, s18, s42
	s_mov_b32 m0, s14
	ds_read_b128 v[186:189], v172 offset:49152
	ds_read_b128 v[190:193], v172 offset:50176
	ds_read_b128 v[194:197], v172 offset:51200
	ds_read_b128 v[198:201], v172 offset:52224
	ds_read_b128 v[202:205], v172 offset:53248
	ds_read_b128 v[206:209], v172 offset:54272
	ds_read_b128 v[210:213], v172 offset:55296
	ds_read_b128 v[214:217], v172 offset:56320
	s_add_u32 vcc_lo, s10, 0x80
	s_addc_u32 vcc_hi, s11, 0
	global_load_lds_dwordx4 v142, vcc
	s_add_i32 m0, s14, 0x2000
	s_add_u32 s10, s10, 0x100080
	s_addc_u32 s11, s11, 0
	s_add_i32 s14, s19, s42
	global_load_lds_dwordx4 v138, vcc
	s_mov_b32 m0, s14
	s_nop 0
	global_load_lds_dwordx4 v142, s[10:11]
	s_add_i32 m0, s14, 0x2000
	s_nop 0
	global_load_lds_dwordx4 v138, s[10:11]
	s_mov_b32 m0, s73
	s_nop 0
	global_load_lds_dwordx4 v144, s[100:101]
	s_mov_b32 m0, s82
	s_nop 0
	global_load_lds_dwordx4 v140, s[100:101]
	s_waitcnt vmcnt(8)
	s_waitcnt lgkmcnt(0)
	s_setprio 1
	s_barrier
	v_mfma_f32_16x16x32_bf16 v[62:65], v[130:133], v[186:189], v[62:65]
	v_mfma_f32_16x16x32_bf16 v[58:61], v[152:155], v[186:189], v[58:61]
	v_mfma_f32_16x16x32_bf16 v[46:49], v[130:133], v[194:197], v[46:49]
	v_mfma_f32_16x16x32_bf16 v[42:45], v[152:155], v[194:197], v[42:45]
	v_mfma_f32_16x16x32_bf16 v[30:33], v[130:133], v[202:205], v[30:33]
	v_mfma_f32_16x16x32_bf16 v[26:29], v[152:155], v[202:205], v[26:29]
	v_mfma_f32_16x16x32_bf16 v[12:15], v[130:133], v[210:213], v[12:15]
	v_mfma_f32_16x16x32_bf16 v[8:11], v[152:155], v[210:213], v[8:11]
	v_mfma_f32_16x16x32_bf16 v[62:65], v[134:137], v[190:193], v[62:65]
	v_mfma_f32_16x16x32_bf16 v[58:61], v[156:159], v[190:193], v[58:61]
	v_mfma_f32_16x16x32_bf16 v[46:49], v[134:137], v[198:201], v[46:49]
	v_mfma_f32_16x16x32_bf16 v[42:45], v[156:159], v[198:201], v[42:45]
	v_mfma_f32_16x16x32_bf16 v[30:33], v[134:137], v[206:209], v[30:33]
	v_mfma_f32_16x16x32_bf16 v[26:29], v[156:159], v[206:209], v[26:29]
	v_mfma_f32_16x16x32_bf16 v[12:15], v[134:137], v[214:217], v[12:15]
	v_mfma_f32_16x16x32_bf16 v[8:11], v[156:159], v[214:217], v[8:11]
	v_mfma_f32_16x16x32_bf16 v[54:57], v[160:163], v[186:189], v[54:57]
	v_mfma_f32_16x16x32_bf16 v[50:53], v[178:181], v[186:189], v[50:53]
	v_mfma_f32_16x16x32_bf16 v[38:41], v[160:163], v[194:197], v[38:41]
	v_mfma_f32_16x16x32_bf16 v[34:37], v[178:181], v[194:197], v[34:37]
	v_mfma_f32_16x16x32_bf16 v[22:25], v[160:163], v[202:205], v[22:25]
	v_mfma_f32_16x16x32_bf16 v[18:21], v[178:181], v[202:205], v[18:21]
	v_mfma_f32_16x16x32_bf16 v[4:7], v[160:163], v[210:213], v[4:7]
	v_mfma_f32_16x16x32_bf16 v[0:3], v[178:181], v[210:213], v[0:3]
	v_mfma_f32_16x16x32_bf16 v[54:57], v[174:177], v[190:193], v[54:57]
	v_mfma_f32_16x16x32_bf16 v[50:53], v[182:185], v[190:193], v[50:53]
	v_mfma_f32_16x16x32_bf16 v[38:41], v[174:177], v[198:201], v[38:41]
	v_mfma_f32_16x16x32_bf16 v[34:37], v[182:185], v[198:201], v[34:37]
	v_mfma_f32_16x16x32_bf16 v[22:25], v[174:177], v[206:209], v[22:25]
	v_mfma_f32_16x16x32_bf16 v[18:21], v[182:185], v[206:209], v[18:21]
	v_mfma_f32_16x16x32_bf16 v[4:7], v[174:177], v[214:217], v[4:7]
	v_mfma_f32_16x16x32_bf16 v[0:3], v[182:185], v[214:217], v[0:3]
	s_barrier
	s_setprio 0
	s_add_i32 s27, s27, 2
	s_add_u32 s8, s8, 0x100
	s_addc_u32 s9, s9, 0
	s_add_u32 s0, s0, 0x100
	s_addc_u32 s1, s1, 0
	s_cmp_gt_u32 s27, 61
	s_cbranch_scc0 .LBB0_129
	s_and_b64 vcc, exec, s[24:25]
	s_cbranch_vccz .LBB0_132
	s_barrier

; #define PG8_STAGEA(bufoff, gbase, voff) PG8_STAGE_X(bufoff, gbase, voff, AUXA)
; #define PG8_LDA(dst, b, h) do { _Pragma("unroll") for (int m = 0; m < 4; ++m) _Pragma("unroll") for (int k = 0; k < 2; ++k) dst[m][k] = *(const PG8_LAS bf16x8*)(lds + PG8_SA(b, h) + aoff + m * 2048 + k * 1024); } while (0)
; #define PG8_LDB(dst, b, h) do { _Pragma("unroll") for (int n = 0; n < 2; ++n) _Pragma("unroll") for (int k = 0; k < 2; ++k) dst[n][k] = *(const PG8_LAS bf16x8*)(lds + PG8_SB(b, h) + boff + n * 2048 + k * 1024); } while (0)
; #define PG8_MMA(ai, bj, At, Bt) do { if (GEMM_PRIO_MODE == 0) __builtin_amdgcn_s_setprio(1); PG8_MMA_LOOPS \
;         acc[ai][bj][m][n] = __builtin_amdgcn_mfma_f32_16x16x32_bf16(Bt[n][k], At[m][k], acc[ai][bj][m][n], 0, 0, 0); if (GEMM_PRIO_MODE == 0) __builtin_amdgcn_s_setprio(0); } while (0)
; #define PG8_WAIT_V(n) asm volatile("s_waitcnt vmcnt(" #n ")" ::: "memory")
; #define PG8_WAIT_VR(n, nr, flag) asm volatile("s_cmp_eq_u32 %0, 0\n\ts_cbranch_scc1 .Lpg8s%=\n\ts_waitcnt vmcnt(" #nr ")\n\ts_branch .Lpg8d%=\n.Lpg8s%=:\n\ts_waitcnt vmcnt(" #n ")\n.Lpg8d%=:" :: "s"(flag) : "memory", "scc")
;     ...
;         for (int t = t0; t < nt; t += 2) {
;             const bool last = (t == nt - 2);
;             const char* a1 = cA + (size_t)(t + 1) * kstepA;
;             const char* a2 = last ? nA : cA + (size_t)(t + 2) * kstepA; const char* b2 = last ? nB : cB + (size_t)(t + 2) * kstepB;
;             const char* a3 = a2 + kstepA; const char* b3 = b2 + kstepB;
;             if (last && has_next) S.a_ready(nxt);
;             if constexpr (SP2) {
;             PG8_LDB(B0, 0, 0); PG8_LDB(B1, 0, 1); PG8_SCHED; PG8_LDA(At, 0, 0); PG8_STAGEA(PG8_SA(1, 1), a1 + hstepA, voffA);
;     ...
;             const int relax = __builtin_amdgcn_readfirstlane((t == 0 && ui > 0) ? 1 : 0);
;             PG8_WAIT_VR(8, 24, relax); PG8_WAIT_L(0); PG8_BAR; PG8_MMA(0, 0, At, B0); PG8_MMA(0, 1, At, B1); PG8_BAR; PG8_SCHED;
;     ...
;             PG8_WAIT_V(8); PG8_WAIT_L(0); PG8_BAR; PG8_MMA(0, 0, At, B0); PG8_MMA(0, 1, At, B1); PG8_BAR; PG8_SCHED;
;     ...
; #pragma unroll
;         for (int a = 0; a < 2; ++a)
; #pragma unroll
;             for (int b = 0; b < 2; ++b)
; #pragma unroll
;                 for (int m = 0; m < 4; ++m)
; #pragma unroll
;                     for (int n = 0; n < 2; ++n) acc[a][b][m][n] = (f32x4){0.f, 0.f, 0.f, 0.f};
;         cur = nxt; cA = nA; cB = nB; ++ui;
.LBB0_557:
	s_ashr_i32 s21, s20, 31
	s_lshl_b64 s[6:7], s[20:21], 21
	s_add_u32 s24, s60, s6
	s_addc_u32 s25, s61, s7
	s_and_b64 s[6:7], s[26:27], exec
	s_cselect_b32 s21, s25, s1
	s_cselect_b32 s82, s24, s0
	s_ashr_i32 s23, s22, 31
	s_lshl_b64 s[6:7], s[22:23], 21
	s_add_u32 s36, s4, s6
	s_addc_u32 s37, s5, s7
	s_and_b64 s[6:7], s[26:27], exec
	s_cselect_b32 s23, s37, s41
	s_cselect_b32 s83, s36, s40
	s_add_u32 s38, s0, 0x100080
	s_addc_u32 s39, s1, 0
	s_add_u32 s0, s40, 0x100
	v_mov_b32_e32 v0, 0
	s_addc_u32 s1, s41, 0
	s_mov_b32 s90, -2
	s_waitcnt lgkmcnt(0)
	v_mov_b32_e32 v1, v0
	v_mov_b32_e32 v2, v0
	v_mov_b32_e32 v3, v0
	v_mov_b32_e32 v4, v0
	v_mov_b32_e32 v5, v0
	v_mov_b32_e32 v6, v0
	v_mov_b32_e32 v7, v0
	v_mov_b32_e32 v18, v0
	v_mov_b32_e32 v19, v0
	v_mov_b32_e32 v20, v0
	v_mov_b32_e32 v21, v0
	s_waitcnt vmcnt(0)
	v_mov_b32_e32 v22, v0
	v_mov_b32_e32 v23, v0
	v_mov_b32_e32 v24, v0
	v_mov_b32_e32 v25, v0
	v_mov_b32_e32 v34, v0
	v_mov_b32_e32 v35, v0
	v_mov_b32_e32 v36, v0
	v_mov_b32_e32 v37, v0
	v_mov_b32_e32 v38, v0
	v_mov_b32_e32 v39, v0
	v_mov_b32_e32 v40, v0
	v_mov_b32_e32 v41, v0
	v_mov_b32_e32 v50, v0
	v_mov_b32_e32 v51, v0
	v_mov_b32_e32 v52, v0
	v_mov_b32_e32 v53, v0
	v_mov_b32_e32 v54, v0
	v_mov_b32_e32 v55, v0
	v_mov_b32_e32 v56, v0
	v_mov_b32_e32 v57, v0
	v_mov_b32_e32 v8, v0
	v_mov_b32_e32 v9, v0
	v_mov_b32_e32 v10, v0
	v_mov_b32_e32 v11, v0
	v_mov_b32_e32 v12, v0
	v_mov_b32_e32 v13, v0
	v_mov_b32_e32 v14, v0
	v_mov_b32_e32 v15, v0
	v_mov_b32_e32 v26, v0
	v_mov_b32_e32 v27, v0
	v_mov_b32_e32 v28, v0
	v_mov_b32_e32 v29, v0
	v_mov_b32_e32 v30, v0
	v_mov_b32_e32 v31, v0
	v_mov_b32_e32 v32, v0
	v_mov_b32_e32 v33, v0
	v_mov_b32_e32 v42, v0
	v_mov_b32_e32 v43, v0
	v_mov_b32_e32 v44, v0
	v_mov_b32_e32 v45, v0
	v_mov_b32_e32 v46, v0
	v_mov_b32_e32 v47, v0
	v_mov_b32_e32 v48, v0
	v_mov_b32_e32 v49, v0
	v_mov_b32_e32 v58, v0
	v_mov_b32_e32 v59, v0
	v_mov_b32_e32 v60, v0
	v_mov_b32_e32 v61, v0
	v_mov_b32_e32 v62, v0
	v_mov_b32_e32 v63, v0
	v_mov_b32_e32 v64, v0
	v_mov_b32_e32 v65, v0
	v_mov_b32_e32 v66, v0
	v_mov_b32_e32 v67, v0
	v_mov_b32_e32 v68, v0
	v_mov_b32_e32 v69, v0
	v_mov_b32_e32 v70, v0
	v_mov_b32_e32 v71, v0
	v_mov_b32_e32 v72, v0
	v_mov_b32_e32 v73, v0
	v_mov_b32_e32 v82, v0
	v_mov_b32_e32 v83, v0
	v_mov_b32_e32 v84, v0
	v_mov_b32_e32 v85, v0
	v_mov_b32_e32 v86, v0
	v_mov_b32_e32 v87, v0
	v_mov_b32_e32 v88, v0
	v_mov_b32_e32 v89, v0
	v_mov_b32_e32 v98, v0
	v_mov_b32_e32 v99, v0
	v_mov_b32_e32 v100, v0
	v_mov_b32_e32 v101, v0
	v_mov_b32_e32 v102, v0
	v_mov_b32_e32 v103, v0
	v_mov_b32_e32 v104, v0
	v_mov_b32_e32 v105, v0
	v_mov_b32_e32 v114, v0
	v_mov_b32_e32 v115, v0
	v_mov_b32_e32 v116, v0
	v_mov_b32_e32 v117, v0
	v_mov_b32_e32 v118, v0
	v_mov_b32_e32 v119, v0
	v_mov_b32_e32 v120, v0
	v_mov_b32_e32 v121, v0
	v_mov_b32_e32 v74, v0
	v_mov_b32_e32 v75, v0
	v_mov_b32_e32 v76, v0
	v_mov_b32_e32 v77, v0
	v_mov_b32_e32 v78, v0
	v_mov_b32_e32 v79, v0
	v_mov_b32_e32 v80, v0
	v_mov_b32_e32 v81, v0
	v_mov_b32_e32 v90, v0
	v_mov_b32_e32 v91, v0
	v_mov_b32_e32 v92, v0
	v_mov_b32_e32 v93, v0
	v_mov_b32_e32 v94, v0
	v_mov_b32_e32 v95, v0
	v_mov_b32_e32 v96, v0
	v_mov_b32_e32 v97, v0
	v_mov_b32_e32 v106, v0
	v_mov_b32_e32 v107, v0
	v_mov_b32_e32 v108, v0
	v_mov_b32_e32 v109, v0
	v_mov_b32_e32 v110, v0
	v_mov_b32_e32 v111, v0
	v_mov_b32_e32 v112, v0
	v_mov_b32_e32 v113, v0
	v_mov_b32_e32 v122, v0
	v_mov_b32_e32 v123, v0
	v_mov_b32_e32 v124, v0
	v_mov_b32_e32 v125, v0
	v_mov_b32_e32 v126, v0
	v_mov_b32_e32 v127, v0
	v_mov_b32_e32 v128, v0
	v_mov_b32_e32 v129, v0
	v_add_u32_e32 v220, 0x10000, v157
.LBB0_558:
	s_add_u32 s6, s38, 0xfff00080
	s_addc_u32 s7, s39, -1
	s_add_i32 s91, 0, 0x10000
	s_cmp_eq_u32 s90, 60
	s_cselect_b32 s41, s21, s7
	s_cselect_b32 s40, s82, s6
	s_cselect_b32 s17, s23, s1
	s_cselect_b32 s16, s83, s0
	s_add_i32 s94, 0, 0x14000
	ds_read_b128 v[130:133], v220
	ds_read_b128 v[134:137], v220 offset:1024
	ds_read_b128 v[148:151], v220 offset:2048
	ds_read_b128 v[152:155], v220 offset:3072
	ds_read_b128 v[162:165], v220 offset:16384
	ds_read_b128 v[166:169], v220 offset:17408
	ds_read_b128 v[170:173], v220 offset:18432
	ds_read_b128 v[174:177], v220 offset:19456
	s_add_i32 m0, s13, 0xc000
	ds_read_b128 v[178:181], v161
	ds_read_b128 v[182:185], v161 offset:1024
	ds_read_b128 v[186:189], v161 offset:2048
	ds_read_b128 v[190:193], v161 offset:3072
	ds_read_b128 v[194:197], v161 offset:4096
	ds_read_b128 v[198:201], v161 offset:5120
	ds_read_b128 v[202:205], v161 offset:6144
	ds_read_b128 v[206:209], v161 offset:7168
	global_load_lds_dwordx4 v144, s[38:39]
	s_add_i32 m0, s13, 0xe000
	s_nop 0
	global_load_lds_dwordx4 v146, s[38:39]
	s_waitcnt vmcnt(8)
	s_waitcnt lgkmcnt(0)
	s_setprio 1
	s_barrier
; #define PG8_STAGEA(bufoff, gbase, voff) PG8_STAGE_X(bufoff, gbase, voff, AUXA)
; #define PG8_STAGEB(bufoff, gbase, voff) PG8_STAGE_X(bufoff, gbase, voff, AUXB)
; #define PG8_LDA(dst, b, h) do { _Pragma("unroll") for (int m = 0; m < 4; ++m) _Pragma("unroll") for (int k = 0; k < 2; ++k) dst[m][k] = *(const PG8_LAS bf16x8*)(lds + PG8_SA(b, h) + aoff + m * 2048 + k * 1024); } while (0)
; #define PG8_MMA(ai, bj, At, Bt) do { if (GEMM_PRIO_MODE == 0) __builtin_amdgcn_s_setprio(1); PG8_MMA_LOOPS \
;         acc[ai][bj][m][n] = __builtin_amdgcn_mfma_f32_16x16x32_bf16(Bt[n][k], At[m][k], acc[ai][bj][m][n], 0, 0, 0); if (GEMM_PRIO_MODE == 0) __builtin_amdgcn_s_setprio(0); } while (0)
; #define PG8_WAIT_V(n) asm volatile("s_waitcnt vmcnt(" #n ")" ::: "memory")
; #define PG8_WAIT_VR(n, nr, flag) asm volatile("s_cmp_eq_u32 %0, 0\n\ts_cbranch_scc1 .Lpg8s%=\n\ts_waitcnt vmcnt(" #nr ")\n\ts_branch .Lpg8d%=\n.Lpg8s%=:\n\ts_waitcnt vmcnt(" #n ")\n.Lpg8d%=:" :: "s"(flag) : "memory", "scc")
; #define PG8_WAIT_L(n) asm volatile("s_waitcnt lgkmcnt(" #n ")" ::: "memory")
; #define PG8_BAR __builtin_amdgcn_s_barrier()
; #define PG8_SCHED __builtin_amdgcn_sched_barrier(0)
;     ...
;             PG8_WAIT_V(8); PG8_WAIT_L(0); PG8_BAR; PG8_MMA(0, 0, At, B0); PG8_MMA(0, 1, At, B1); PG8_BAR; PG8_SCHED;
;     ...
;             PG8_LDA(At, 0, 1); PG8_STAGEB(PG8_SB(0, 0), b2, voffB); PG8_STAGEB(PG8_SB(0, 1), b2 + hstepB, voffB); PG8_STAGEA(PG8_SA(0, 0), a2, voffA);
;     ...
;             PG8_WAIT_VR(8, 24, relax); PG8_WAIT_L(0); PG8_BAR; PG8_MMA(1, 0, At, B0); PG8_MMA(1, 1, At, B1); PG8_BAR; PG8_SCHED;
;     ...
;             PG8_WAIT_V(8); PG8_WAIT_L(0); PG8_BAR; PG8_MMA(1, 0, At, B0); PG8_MMA(1, 1, At, B1); PG8_BAR; PG8_SCHED;
	v_mfma_f32_16x16x32_bf16 v[126:129], v[130:133], v[178:181], v[126:129]
	v_mfma_f32_16x16x32_bf16 v[122:125], v[148:151], v[178:181], v[122:125]
	v_mfma_f32_16x16x32_bf16 v[110:113], v[130:133], v[186:189], v[110:113]
	v_mfma_f32_16x16x32_bf16 v[106:109], v[148:151], v[186:189], v[106:109]
	v_mfma_f32_16x16x32_bf16 v[94:97], v[130:133], v[194:197], v[94:97]
	v_mfma_f32_16x16x32_bf16 v[90:93], v[148:151], v[194:197], v[90:93]
	v_mfma_f32_16x16x32_bf16 v[78:81], v[130:133], v[202:205], v[78:81]
	v_mfma_f32_16x16x32_bf16 v[74:77], v[148:151], v[202:205], v[74:77]
	v_mfma_f32_16x16x32_bf16 v[126:129], v[134:137], v[182:185], v[126:129]
	v_mfma_f32_16x16x32_bf16 v[122:125], v[152:155], v[182:185], v[122:125]
	v_mfma_f32_16x16x32_bf16 v[110:113], v[134:137], v[190:193], v[110:113]
	v_mfma_f32_16x16x32_bf16 v[106:109], v[152:155], v[190:193], v[106:109]
	v_mfma_f32_16x16x32_bf16 v[94:97], v[134:137], v[198:201], v[94:97]
	v_mfma_f32_16x16x32_bf16 v[90:93], v[152:155], v[198:201], v[90:93]
	v_mfma_f32_16x16x32_bf16 v[78:81], v[134:137], v[206:209], v[78:81]
	v_mfma_f32_16x16x32_bf16 v[74:77], v[152:155], v[206:209], v[74:77]
	v_mfma_f32_16x16x32_bf16 v[118:121], v[162:165], v[178:181], v[118:121]
	v_mfma_f32_16x16x32_bf16 v[114:117], v[170:173], v[178:181], v[114:117]
	v_mfma_f32_16x16x32_bf16 v[102:105], v[162:165], v[186:189], v[102:105]
	v_mfma_f32_16x16x32_bf16 v[98:101], v[170:173], v[186:189], v[98:101]
	v_mfma_f32_16x16x32_bf16 v[86:89], v[162:165], v[194:197], v[86:89]
	v_mfma_f32_16x16x32_bf16 v[82:85], v[170:173], v[194:197], v[82:85]
	v_mfma_f32_16x16x32_bf16 v[70:73], v[162:165], v[202:205], v[70:73]
	v_mfma_f32_16x16x32_bf16 v[66:69], v[170:173], v[202:205], v[66:69]
	v_mfma_f32_16x16x32_bf16 v[118:121], v[166:169], v[182:185], v[118:121]
	v_mfma_f32_16x16x32_bf16 v[114:117], v[174:177], v[182:185], v[114:117]
	v_mfma_f32_16x16x32_bf16 v[102:105], v[166:169], v[190:193], v[102:105]
	v_mfma_f32_16x16x32_bf16 v[98:101], v[174:177], v[190:193], v[98:101]
	v_mfma_f32_16x16x32_bf16 v[86:89], v[166:169], v[198:201], v[86:89]
	v_mfma_f32_16x16x32_bf16 v[82:85], v[174:177], v[198:201], v[82:85]
	v_mfma_f32_16x16x32_bf16 v[70:73], v[166:169], v[206:209], v[70:73]
	v_mfma_f32_16x16x32_bf16 v[66:69], v[174:177], v[206:209], v[66:69]
	s_barrier
	s_setprio 0
	s_add_i32 s6, s91, s12
	s_mov_b32 m0, s6
	ds_read_b128 v[178:181], v161 offset:16384
	ds_read_b128 v[182:185], v161 offset:17408
	ds_read_b128 v[186:189], v161 offset:18432
	ds_read_b128 v[190:193], v161 offset:19456
	ds_read_b128 v[194:197], v161 offset:20480
	ds_read_b128 v[198:201], v161 offset:21504
	ds_read_b128 v[202:205], v161 offset:22528
	ds_read_b128 v[206:209], v161 offset:23552
	global_load_lds_dwordx4 v16, s[16:17]
	s_add_i32 m0, s6, 0x2000
	s_add_u32 s6, s16, 0x100000
	s_addc_u32 s7, s17, 0
	s_add_i32 s91, s94, s12
	global_load_lds_dwordx4 v138, s[16:17]
	s_mov_b32 m0, s91
	s_nop 0
	global_load_lds_dwordx4 v16, s[6:7]
	s_add_i32 m0, s91, 0x2000
	s_nop 0
	global_load_lds_dwordx4 v138, s[6:7]
	s_mov_b32 m0, s13
	s_nop 0
	global_load_lds_dwordx4 v142, s[40:41]
	s_mov_b32 m0, s42
	s_nop 0
	global_load_lds_dwordx4 v140, s[40:41]
	s_waitcnt vmcnt(8)
	s_waitcnt lgkmcnt(0)
	s_setprio 1
	s_barrier
	v_mfma_f32_16x16x32_bf16 v[62:65], v[130:133], v[178:181], v[62:65]
	v_mfma_f32_16x16x32_bf16 v[58:61], v[148:151], v[178:181], v[58:61]
	v_mfma_f32_16x16x32_bf16 v[46:49], v[130:133], v[186:189], v[46:49]
	v_mfma_f32_16x16x32_bf16 v[42:45], v[148:151], v[186:189], v[42:45]
	v_mfma_f32_16x16x32_bf16 v[30:33], v[130:133], v[194:197], v[30:33]
	v_mfma_f32_16x16x32_bf16 v[26:29], v[148:151], v[194:197], v[26:29]
	v_mfma_f32_16x16x32_bf16 v[12:15], v[130:133], v[202:205], v[12:15]
	v_mfma_f32_16x16x32_bf16 v[8:11], v[148:151], v[202:205], v[8:11]
	v_mfma_f32_16x16x32_bf16 v[62:65], v[134:137], v[182:185], v[62:65]
	v_mfma_f32_16x16x32_bf16 v[58:61], v[152:155], v[182:185], v[58:61]
	v_mfma_f32_16x16x32_bf16 v[46:49], v[134:137], v[190:193], v[46:49]
	v_mfma_f32_16x16x32_bf16 v[42:45], v[152:155], v[190:193], v[42:45]
	v_mfma_f32_16x16x32_bf16 v[30:33], v[134:137], v[198:201], v[30:33]
	v_mfma_f32_16x16x32_bf16 v[26:29], v[152:155], v[198:201], v[26:29]
	v_mfma_f32_16x16x32_bf16 v[12:15], v[134:137], v[206:209], v[12:15]
	v_mfma_f32_16x16x32_bf16 v[8:11], v[152:155], v[206:209], v[8:11]
	v_mfma_f32_16x16x32_bf16 v[54:57], v[162:165], v[178:181], v[54:57]
	v_mfma_f32_16x16x32_bf16 v[50:53], v[170:173], v[178:181], v[50:53]
	v_mfma_f32_16x16x32_bf16 v[38:41], v[162:165], v[186:189], v[38:41]
	v_mfma_f32_16x16x32_bf16 v[34:37], v[170:173], v[186:189], v[34:37]
	v_mfma_f32_16x16x32_bf16 v[22:25], v[162:165], v[194:197], v[22:25]
	v_mfma_f32_16x16x32_bf16 v[18:21], v[170:173], v[194:197], v[18:21]
	v_mfma_f32_16x16x32_bf16 v[4:7], v[162:165], v[202:205], v[4:7]
	v_mfma_f32_16x16x32_bf16 v[0:3], v[170:173], v[202:205], v[0:3]
	v_mfma_f32_16x16x32_bf16 v[54:57], v[166:169], v[182:185], v[54:57]
	v_mfma_f32_16x16x32_bf16 v[50:53], v[174:177], v[182:185], v[50:53]
	v_mfma_f32_16x16x32_bf16 v[38:41], v[166:169], v[190:193], v[38:41]
	v_mfma_f32_16x16x32_bf16 v[34:37], v[174:177], v[190:193], v[34:37]
	v_mfma_f32_16x16x32_bf16 v[22:25], v[166:169], v[198:201], v[22:25]
	v_mfma_f32_16x16x32_bf16 v[18:21], v[174:177], v[198:201], v[18:21]
	v_mfma_f32_16x16x32_bf16 v[4:7], v[166:169], v[206:209], v[4:7]
	v_mfma_f32_16x16x32_bf16 v[0:3], v[174:177], v[206:209], v[0:3]
	s_barrier
; #define PG8_STAGEA(bufoff, gbase, voff) PG8_STAGE_X(bufoff, gbase, voff, AUXA)
; #define PG8_STAGEB(bufoff, gbase, voff) PG8_STAGE_X(bufoff, gbase, voff, AUXB)
; #define PG8_LDA(dst, b, h) do { _Pragma("unroll") for (int m = 0; m < 4; ++m) _Pragma("unroll") for (int k = 0; k < 2; ++k) dst[m][k] = *(const PG8_LAS bf16x8*)(lds + PG8_SA(b, h) + aoff + m * 2048 + k * 1024); } while (0)
; #define PG8_LDB(dst, b, h) do { _Pragma("unroll") for (int n = 0; n < 2; ++n) _Pragma("unroll") for (int k = 0; k < 2; ++k) dst[n][k] = *(const PG8_LAS bf16x8*)(lds + PG8_SB(b, h) + boff + n * 2048 + k * 1024); } while (0)
; #define PG8_MMA(ai, bj, At, Bt) do { if (GEMM_PRIO_MODE == 0) __builtin_amdgcn_s_setprio(1); PG8_MMA_LOOPS \
;         acc[ai][bj][m][n] = __builtin_amdgcn_mfma_f32_16x16x32_bf16(Bt[n][k], At[m][k], acc[ai][bj][m][n], 0, 0, 0); if (GEMM_PRIO_MODE == 0) __builtin_amdgcn_s_setprio(0); } while (0)
; #define PG8_WAIT_V(n) asm volatile("s_waitcnt vmcnt(" #n ")" ::: "memory")
; #define PG8_WAIT_L(n) asm volatile("s_waitcnt lgkmcnt(" #n ")" ::: "memory")
; #define PG8_BAR __builtin_amdgcn_s_barrier()
; #define PG8_SCHED __builtin_amdgcn_sched_barrier(0)
;     ...
;             PG8_LDB(B0, 1, 0); PG8_LDB(B1, 1, 1); PG8_SCHED; PG8_LDA(At, 1, 0); PG8_STAGEA(PG8_SA(0, 1), a2 + hstepA, voffA);
;             PG8_WAIT_V(8); PG8_WAIT_L(0); PG8_BAR; PG8_MMA(0, 0, At, B0); PG8_MMA(0, 1, At, B1); PG8_BAR; PG8_SCHED;
;             PG8_LDA(At, 1, 1); PG8_STAGEB(PG8_SB(1, 0), b3, voffB); PG8_STAGEB(PG8_SB(1, 1), b3 + hstepB, voffB); PG8_STAGEA(PG8_SA(1, 0), a3, voffA);
;             PG8_WAIT_V(8); PG8_WAIT_L(0); PG8_BAR; PG8_MMA(1, 0, At, B0); PG8_MMA(1, 1, At, B1); PG8_BAR; PG8_SCHED;
	s_setprio 0
	s_add_i32 s91, 0, 0x18000
	s_add_i32 s94, 0, 0x1c000
	ds_read_b128 v[130:133], v220 offset:32768
	ds_read_b128 v[134:137], v220 offset:33792
	ds_read_b128 v[148:151], v220 offset:34816
	ds_read_b128 v[152:155], v220 offset:35840
	ds_read_b128 v[162:165], v220 offset:49152
	ds_read_b128 v[166:169], v220 offset:50176
	ds_read_b128 v[170:173], v220 offset:51200
	ds_read_b128 v[174:177], v220 offset:52224
	s_add_u32 s6, s40, 0x100000
	s_addc_u32 s7, s41, 0
	s_mov_b32 m0, s43
	ds_read_b128 v[178:181], v161 offset:32768
	ds_read_b128 v[182:185], v161 offset:33792
	ds_read_b128 v[186:189], v161 offset:34816
	ds_read_b128 v[190:193], v161 offset:35840
	ds_read_b128 v[194:197], v161 offset:36864
	ds_read_b128 v[198:201], v161 offset:37888
	ds_read_b128 v[202:205], v161 offset:38912
	ds_read_b128 v[206:209], v161 offset:39936
	global_load_lds_dwordx4 v142, s[6:7]
	s_mov_b32 m0, s50
	s_nop 0
	global_load_lds_dwordx4 v140, s[6:7]
	s_waitcnt vmcnt(8)
	s_waitcnt lgkmcnt(0)
	s_setprio 1
	s_barrier
	v_mfma_f32_16x16x32_bf16 v[126:129], v[130:133], v[178:181], v[126:129]
	v_mfma_f32_16x16x32_bf16 v[122:125], v[148:151], v[178:181], v[122:125]
	v_mfma_f32_16x16x32_bf16 v[110:113], v[130:133], v[186:189], v[110:113]
	v_mfma_f32_16x16x32_bf16 v[106:109], v[148:151], v[186:189], v[106:109]
	v_mfma_f32_16x16x32_bf16 v[94:97], v[130:133], v[194:197], v[94:97]
	v_mfma_f32_16x16x32_bf16 v[90:93], v[148:151], v[194:197], v[90:93]
	v_mfma_f32_16x16x32_bf16 v[78:81], v[130:133], v[202:205], v[78:81]
	v_mfma_f32_16x16x32_bf16 v[74:77], v[148:151], v[202:205], v[74:77]
	v_mfma_f32_16x16x32_bf16 v[126:129], v[134:137], v[182:185], v[126:129]
	v_mfma_f32_16x16x32_bf16 v[122:125], v[152:155], v[182:185], v[122:125]
	v_mfma_f32_16x16x32_bf16 v[110:113], v[134:137], v[190:193], v[110:113]
	v_mfma_f32_16x16x32_bf16 v[106:109], v[152:155], v[190:193], v[106:109]
	v_mfma_f32_16x16x32_bf16 v[94:97], v[134:137], v[198:201], v[94:97]
	v_mfma_f32_16x16x32_bf16 v[90:93], v[152:155], v[198:201], v[90:93]
	v_mfma_f32_16x16x32_bf16 v[78:81], v[134:137], v[206:209], v[78:81]
	v_mfma_f32_16x16x32_bf16 v[74:77], v[152:155], v[206:209], v[74:77]
	v_mfma_f32_16x16x32_bf16 v[118:121], v[162:165], v[178:181], v[118:121]
	v_mfma_f32_16x16x32_bf16 v[114:117], v[170:173], v[178:181], v[114:117]
	v_mfma_f32_16x16x32_bf16 v[102:105], v[162:165], v[186:189], v[102:105]
	v_mfma_f32_16x16x32_bf16 v[98:101], v[170:173], v[186:189], v[98:101]
	v_mfma_f32_16x16x32_bf16 v[86:89], v[162:165], v[194:197], v[86:89]
	v_mfma_f32_16x16x32_bf16 v[82:85], v[170:173], v[194:197], v[82:85]
	v_mfma_f32_16x16x32_bf16 v[70:73], v[162:165], v[202:205], v[70:73]
	v_mfma_f32_16x16x32_bf16 v[66:69], v[170:173], v[202:205], v[66:69]
	v_mfma_f32_16x16x32_bf16 v[118:121], v[166:169], v[182:185], v[118:121]
	v_mfma_f32_16x16x32_bf16 v[114:117], v[174:177], v[182:185], v[114:117]
	v_mfma_f32_16x16x32_bf16 v[102:105], v[166:169], v[190:193], v[102:105]
	v_mfma_f32_16x16x32_bf16 v[98:101], v[174:177], v[190:193], v[98:101]
	v_mfma_f32_16x16x32_bf16 v[86:89], v[166:169], v[198:201], v[86:89]
	v_mfma_f32_16x16x32_bf16 v[82:85], v[174:177], v[198:201], v[82:85]
	v_mfma_f32_16x16x32_bf16 v[70:73], v[166:169], v[206:209], v[70:73]
	v_mfma_f32_16x16x32_bf16 v[66:69], v[174:177], v[206:209], v[66:69]
	s_barrier
	s_setprio 0
	s_add_i32 s6, s91, s12
	s_mov_b32 m0, s6
	ds_read_b128 v[178:181], v161 offset:49152
	ds_read_b128 v[182:185], v161 offset:50176
	ds_read_b128 v[186:189], v161 offset:51200
	ds_read_b128 v[190:193], v161 offset:52224
	ds_read_b128 v[194:197], v161 offset:53248
	ds_read_b128 v[198:201], v161 offset:54272
	ds_read_b128 v[202:205], v161 offset:55296
	ds_read_b128 v[206:209], v161 offset:56320
	s_add_u32 s100, s16, 0x80
	s_addc_u32 s101, s17, 0
	global_load_lds_dwordx4 v16, s[100:101]
	s_add_i32 m0, s6, 0x2000
	s_add_u32 s6, s16, 0x100080
	s_addc_u32 s7, s17, 0
	s_add_i32 s16, s94, s12
	global_load_lds_dwordx4 v138, s[100:101]
	s_mov_b32 m0, s16
	s_nop 0
	global_load_lds_dwordx4 v16, s[6:7]
	s_add_i32 m0, s16, 0x2000
	s_nop 0
	global_load_lds_dwordx4 v138, s[6:7]
	s_mov_b32 m0, s68
	s_nop 0
	s_add_u32 vcc_lo, s40, 0x80
	s_addc_u32 vcc_hi, s41, 0
	global_load_lds_dwordx4 v142, vcc
	s_mov_b32 m0, s69
	s_nop 0
	global_load_lds_dwordx4 v140, vcc
	s_waitcnt vmcnt(8)
	s_waitcnt lgkmcnt(0)
	s_setprio 1
	s_barrier
	v_mfma_f32_16x16x32_bf16 v[62:65], v[130:133], v[178:181], v[62:65]
	v_mfma_f32_16x16x32_bf16 v[58:61], v[148:151], v[178:181], v[58:61]
	v_mfma_f32_16x16x32_bf16 v[46:49], v[130:133], v[186:189], v[46:49]
	v_mfma_f32_16x16x32_bf16 v[42:45], v[148:151], v[186:189], v[42:45]
	v_mfma_f32_16x16x32_bf16 v[30:33], v[130:133], v[194:197], v[30:33]
	v_mfma_f32_16x16x32_bf16 v[26:29], v[148:151], v[194:197], v[26:29]
	v_mfma_f32_16x16x32_bf16 v[12:15], v[130:133], v[202:205], v[12:15]
	v_mfma_f32_16x16x32_bf16 v[8:11], v[148:151], v[202:205], v[8:11]
	v_mfma_f32_16x16x32_bf16 v[62:65], v[134:137], v[182:185], v[62:65]
	v_mfma_f32_16x16x32_bf16 v[58:61], v[152:155], v[182:185], v[58:61]
	v_mfma_f32_16x16x32_bf16 v[46:49], v[134:137], v[190:193], v[46:49]
	v_mfma_f32_16x16x32_bf16 v[42:45], v[152:155], v[190:193], v[42:45]
	v_mfma_f32_16x16x32_bf16 v[30:33], v[134:137], v[198:201], v[30:33]
	v_mfma_f32_16x16x32_bf16 v[26:29], v[152:155], v[198:201], v[26:29]
	v_mfma_f32_16x16x32_bf16 v[12:15], v[134:137], v[206:209], v[12:15]
	v_mfma_f32_16x16x32_bf16 v[8:11], v[152:155], v[206:209], v[8:11]
	v_mfma_f32_16x16x32_bf16 v[54:57], v[162:165], v[178:181], v[54:57]
	v_mfma_f32_16x16x32_bf16 v[50:53], v[170:173], v[178:181], v[50:53]
	v_mfma_f32_16x16x32_bf16 v[38:41], v[162:165], v[186:189], v[38:41]
	v_mfma_f32_16x16x32_bf16 v[34:37], v[170:173], v[186:189], v[34:37]
	v_mfma_f32_16x16x32_bf16 v[22:25], v[162:165], v[194:197], v[22:25]
	v_mfma_f32_16x16x32_bf16 v[18:21], v[170:173], v[194:197], v[18:21]
	v_mfma_f32_16x16x32_bf16 v[4:7], v[162:165], v[202:205], v[4:7]
	v_mfma_f32_16x16x32_bf16 v[0:3], v[170:173], v[202:205], v[0:3]
	v_mfma_f32_16x16x32_bf16 v[54:57], v[166:169], v[182:185], v[54:57]
	v_mfma_f32_16x16x32_bf16 v[50:53], v[174:177], v[182:185], v[50:53]
	v_mfma_f32_16x16x32_bf16 v[38:41], v[166:169], v[190:193], v[38:41]
	v_mfma_f32_16x16x32_bf16 v[34:37], v[174:177], v[190:193], v[34:37]
	v_mfma_f32_16x16x32_bf16 v[22:25], v[166:169], v[198:201], v[22:25]
	v_mfma_f32_16x16x32_bf16 v[18:21], v[174:177], v[198:201], v[18:21]
	v_mfma_f32_16x16x32_bf16 v[4:7], v[166:169], v[206:209], v[4:7]
	v_mfma_f32_16x16x32_bf16 v[0:3], v[174:177], v[206:209], v[0:3]
	s_barrier
	s_setprio 0
	s_add_i32 s90, s90, 2
	s_add_u32 s38, s38, 0x100
	s_addc_u32 s39, s39, 0
	s_add_u32 s0, s0, 0x100
	s_addc_u32 s1, s1, 0
	s_cmp_gt_u32 s90, 61
	s_cbranch_scc0 .LBB0_558
	s_and_b64 vcc, exec, s[18:19]
	s_cbranch_vccz .LBB0_561
	s_barrier

; #define PG8_STAGEA(bufoff, gbase, voff) PG8_STAGE_X(bufoff, gbase, voff, AUXA)
; #define PG8_LDA(dst, b, h) do { _Pragma("unroll") for (int m = 0; m < 4; ++m) _Pragma("unroll") for (int k = 0; k < 2; ++k) dst[m][k] = *(const PG8_LAS bf16x8*)(lds + PG8_SA(b, h) + aoff + m * 2048 + k * 1024); } while (0)
; #define PG8_LDB(dst, b, h) do { _Pragma("unroll") for (int n = 0; n < 2; ++n) _Pragma("unroll") for (int k = 0; k < 2; ++k) dst[n][k] = *(const PG8_LAS bf16x8*)(lds + PG8_SB(b, h) + boff + n * 2048 + k * 1024); } while (0)
; #define PG8_MMA(ai, bj, At, Bt) do { if (GEMM_PRIO_MODE == 0) __builtin_amdgcn_s_setprio(1); PG8_MMA_LOOPS \
;         acc[ai][bj][m][n] = __builtin_amdgcn_mfma_f32_16x16x32_bf16(Bt[n][k], At[m][k], acc[ai][bj][m][n], 0, 0, 0); if (GEMM_PRIO_MODE == 0) __builtin_amdgcn_s_setprio(0); } while (0)
; #define PG8_WAIT_V(n) asm volatile("s_waitcnt vmcnt(" #n ")" ::: "memory")
; #define PG8_WAIT_VR(n, nr, flag) asm volatile("s_cmp_eq_u32 %0, 0\n\ts_cbranch_scc1 .Lpg8s%=\n\ts_waitcnt vmcnt(" #nr ")\n\ts_branch .Lpg8d%=\n.Lpg8s%=:\n\ts_waitcnt vmcnt(" #n ")\n.Lpg8d%=:" :: "s"(flag) : "memory", "scc")
;     ...
;         for (int t = t0; t < nt; t += 2) {
;             const bool last = (t == nt - 2);
;             const char* a1 = cA + (size_t)(t + 1) * kstepA;
;             const char* a2 = last ? nA : cA + (size_t)(t + 2) * kstepA; const char* b2 = last ? nB : cB + (size_t)(t + 2) * kstepB;
;             const char* a3 = a2 + kstepA; const char* b3 = b2 + kstepB;
;             if (last && has_next) S.a_ready(nxt);
;             if constexpr (SP2) {
;             PG8_LDB(B0, 0, 0); PG8_LDB(B1, 0, 1); PG8_SCHED; PG8_LDA(At, 0, 0); PG8_STAGEA(PG8_SA(1, 1), a1 + hstepA, voffA);
;     ...
;             const int relax = __builtin_amdgcn_readfirstlane((t == 0 && ui > 0) ? 1 : 0);
;             PG8_WAIT_VR(8, 24, relax); PG8_WAIT_L(0); PG8_BAR; PG8_MMA(0, 0, At, B0); PG8_MMA(0, 1, At, B1); PG8_BAR; PG8_SCHED;
;     ...
;             PG8_WAIT_V(8); PG8_WAIT_L(0); PG8_BAR; PG8_MMA(0, 0, At, B0); PG8_MMA(0, 1, At, B1); PG8_BAR; PG8_SCHED;
;     ...
; #pragma unroll
;         for (int a = 0; a < 2; ++a)
; #pragma unroll
;             for (int b = 0; b < 2; ++b)
; #pragma unroll
;                 for (int m = 0; m < 4; ++m)
; #pragma unroll
;                     for (int n = 0; n < 2; ++n) acc[a][b][m][n] = (f32x4){0.f, 0.f, 0.f, 0.f};
;         cur = nxt; cA = nA; cB = nB; ++ui;
.LBB0_711:
	s_ashr_i32 s25, s24, 31
	s_lshl_b64 s[0:1], s[24:25], 21
	s_add_u32 s26, s56, s0
	s_addc_u32 s27, s57, s1
	s_and_b64 s[0:1], s[10:11], exec
	s_cselect_b32 s0, s27, s13
	s_cselect_b32 s1, s26, s12
	s_ashr_i32 s23, s22, 31
	s_lshl_b64 s[6:7], s[22:23], 21
	s_add_u32 s36, s51, s6
	s_addc_u32 s37, s68, s7
	s_and_b64 s[6:7], s[10:11], exec
	s_cselect_b32 s23, s37, s43
	s_cselect_b32 s25, s36, s42
	s_add_u32 s40, s12, 0x100080
	s_addc_u32 s41, s13, 0
	s_add_u32 s12, s42, 0x100
	v_mov_b32_e32 v0, 0
	s_addc_u32 s13, s43, 0
	s_mov_b32 s39, -2
	v_mov_b32_e32 v1, v0
	v_mov_b32_e32 v2, v0
	v_mov_b32_e32 v3, v0
	v_mov_b32_e32 v4, v0
	v_mov_b32_e32 v5, v0
	v_mov_b32_e32 v6, v0
	v_mov_b32_e32 v7, v0
	v_mov_b32_e32 v18, v0
	v_mov_b32_e32 v19, v0
	v_mov_b32_e32 v20, v0
	v_mov_b32_e32 v21, v0
	v_mov_b32_e32 v22, v0
	v_mov_b32_e32 v23, v0
	v_mov_b32_e32 v24, v0
	v_mov_b32_e32 v25, v0
	v_mov_b32_e32 v34, v0
	v_mov_b32_e32 v35, v0
	v_mov_b32_e32 v36, v0
	v_mov_b32_e32 v37, v0
	v_mov_b32_e32 v38, v0
	v_mov_b32_e32 v39, v0
	v_mov_b32_e32 v40, v0
	v_mov_b32_e32 v41, v0
	v_mov_b32_e32 v50, v0
	v_mov_b32_e32 v51, v0
	v_mov_b32_e32 v52, v0
	v_mov_b32_e32 v53, v0
	v_mov_b32_e32 v54, v0
	v_mov_b32_e32 v55, v0
	v_mov_b32_e32 v56, v0
	v_mov_b32_e32 v57, v0
	v_mov_b32_e32 v8, v0
	v_mov_b32_e32 v9, v0
	v_mov_b32_e32 v10, v0
	v_mov_b32_e32 v11, v0
	v_mov_b32_e32 v12, v0
	v_mov_b32_e32 v13, v0
	v_mov_b32_e32 v14, v0
	v_mov_b32_e32 v15, v0
	v_mov_b32_e32 v26, v0
	v_mov_b32_e32 v27, v0
	v_mov_b32_e32 v28, v0
	v_mov_b32_e32 v29, v0
	v_mov_b32_e32 v30, v0
	v_mov_b32_e32 v31, v0
	v_mov_b32_e32 v32, v0
	v_mov_b32_e32 v33, v0
	v_mov_b32_e32 v42, v0
	v_mov_b32_e32 v43, v0
	v_mov_b32_e32 v44, v0
	v_mov_b32_e32 v45, v0
	v_mov_b32_e32 v46, v0
	v_mov_b32_e32 v47, v0
	v_mov_b32_e32 v48, v0
	v_mov_b32_e32 v49, v0
	v_mov_b32_e32 v58, v0
	v_mov_b32_e32 v59, v0
	v_mov_b32_e32 v60, v0
	v_mov_b32_e32 v61, v0
	v_mov_b32_e32 v62, v0
	v_mov_b32_e32 v63, v0
	v_mov_b32_e32 v64, v0
	v_mov_b32_e32 v65, v0
	v_mov_b32_e32 v66, v0
	v_mov_b32_e32 v67, v0
	v_mov_b32_e32 v68, v0
	v_mov_b32_e32 v69, v0
	v_mov_b32_e32 v70, v0
	v_mov_b32_e32 v71, v0
	v_mov_b32_e32 v72, v0
	v_mov_b32_e32 v73, v0
	v_mov_b32_e32 v82, v0
	v_mov_b32_e32 v83, v0
	v_mov_b32_e32 v84, v0
	v_mov_b32_e32 v85, v0
	v_mov_b32_e32 v86, v0
	v_mov_b32_e32 v87, v0
	v_mov_b32_e32 v88, v0
	v_mov_b32_e32 v89, v0
	v_mov_b32_e32 v98, v0
	v_mov_b32_e32 v99, v0
	v_mov_b32_e32 v100, v0
	v_mov_b32_e32 v101, v0
	v_mov_b32_e32 v102, v0
	v_mov_b32_e32 v103, v0
	v_mov_b32_e32 v104, v0
	v_mov_b32_e32 v105, v0
	v_mov_b32_e32 v114, v0
	v_mov_b32_e32 v115, v0
	v_mov_b32_e32 v116, v0
	v_mov_b32_e32 v117, v0
	v_mov_b32_e32 v118, v0
	v_mov_b32_e32 v119, v0
	v_mov_b32_e32 v120, v0
	v_mov_b32_e32 v121, v0
	v_mov_b32_e32 v74, v0
	v_mov_b32_e32 v75, v0
	v_mov_b32_e32 v76, v0
	v_mov_b32_e32 v77, v0
	v_mov_b32_e32 v78, v0
	v_mov_b32_e32 v79, v0
	v_mov_b32_e32 v80, v0
	v_mov_b32_e32 v81, v0
	v_mov_b32_e32 v90, v0
	v_mov_b32_e32 v91, v0
	v_mov_b32_e32 v92, v0
	v_mov_b32_e32 v93, v0
	v_mov_b32_e32 v94, v0
	v_mov_b32_e32 v95, v0
	v_mov_b32_e32 v96, v0
	v_mov_b32_e32 v97, v0
	v_mov_b32_e32 v106, v0
	v_mov_b32_e32 v107, v0
	v_mov_b32_e32 v108, v0
	v_mov_b32_e32 v109, v0
	v_mov_b32_e32 v110, v0
	v_mov_b32_e32 v111, v0
	v_mov_b32_e32 v112, v0
	v_mov_b32_e32 v113, v0
	v_mov_b32_e32 v122, v0
	v_mov_b32_e32 v123, v0
	v_mov_b32_e32 v124, v0
	v_mov_b32_e32 v125, v0
	v_mov_b32_e32 v126, v0
	v_mov_b32_e32 v127, v0
	v_mov_b32_e32 v128, v0
	v_mov_b32_e32 v129, v0
	v_add_u32_e32 v222, 0x10000, v146
.LBB0_712:
	s_add_u32 s6, s40, 0xfff00080
	s_addc_u32 s7, s41, -1
	s_add_i32 s95, 0, 0x10000
	s_cmp_eq_u32 s39, 60
	s_cselect_b32 s43, s0, s7
	s_cselect_b32 s42, s1, s6
	s_cselect_b32 s17, s23, s13
	s_cselect_b32 s16, s25, s12
	s_add_i32 vcc_lo, 0, 0x14000
	ds_read_b128 v[150:153], v222
	ds_read_b128 v[154:157], v222 offset:1024
	ds_read_b128 v[158:161], v222 offset:2048
	ds_read_b128 v[162:165], v222 offset:3072
	ds_read_b128 v[166:169], v222 offset:16384
	ds_read_b128 v[170:173], v222 offset:17408
	ds_read_b128 v[174:177], v222 offset:18432
	ds_read_b128 v[178:181], v222 offset:19456
	s_add_i32 m0, s69, 0xc000
	ds_read_b128 v[182:185], v148
	ds_read_b128 v[186:189], v148 offset:1024
	ds_read_b128 v[190:193], v148 offset:2048
	ds_read_b128 v[194:197], v148 offset:3072
	ds_read_b128 v[198:201], v148 offset:4096
	ds_read_b128 v[202:205], v148 offset:5120
	ds_read_b128 v[206:209], v148 offset:6144
	ds_read_b128 v[210:213], v148 offset:7168
	global_load_lds_dwordx4 v140, s[40:41]
	s_add_i32 m0, s69, 0xe000
	s_nop 0
	global_load_lds_dwordx4 v142, s[40:41]
	s_waitcnt vmcnt(8)
	s_waitcnt lgkmcnt(0)
	s_setprio 1
	s_barrier
; #define PG8_STAGEA(bufoff, gbase, voff) PG8_STAGE_X(bufoff, gbase, voff, AUXA)
; #define PG8_STAGEB(bufoff, gbase, voff) PG8_STAGE_X(bufoff, gbase, voff, AUXB)
; #define PG8_LDA(dst, b, h) do { _Pragma("unroll") for (int m = 0; m < 4; ++m) _Pragma("unroll") for (int k = 0; k < 2; ++k) dst[m][k] = *(const PG8_LAS bf16x8*)(lds + PG8_SA(b, h) + aoff + m * 2048 + k * 1024); } while (0)
; #define PG8_MMA(ai, bj, At, Bt) do { if (GEMM_PRIO_MODE == 0) __builtin_amdgcn_s_setprio(1); PG8_MMA_LOOPS \
;         acc[ai][bj][m][n] = __builtin_amdgcn_mfma_f32_16x16x32_bf16(Bt[n][k], At[m][k], acc[ai][bj][m][n], 0, 0, 0); if (GEMM_PRIO_MODE == 0) __builtin_amdgcn_s_setprio(0); } while (0)
; #define PG8_WAIT_V(n) asm volatile("s_waitcnt vmcnt(" #n ")" ::: "memory")
; #define PG8_WAIT_VR(n, nr, flag) asm volatile("s_cmp_eq_u32 %0, 0\n\ts_cbranch_scc1 .Lpg8s%=\n\ts_waitcnt vmcnt(" #nr ")\n\ts_branch .Lpg8d%=\n.Lpg8s%=:\n\ts_waitcnt vmcnt(" #n ")\n.Lpg8d%=:" :: "s"(flag) : "memory", "scc")
; #define PG8_WAIT_L(n) asm volatile("s_waitcnt lgkmcnt(" #n ")" ::: "memory")
; #define PG8_BAR __builtin_amdgcn_s_barrier()
; #define PG8_SCHED __builtin_amdgcn_sched_barrier(0)
;     ...
;             PG8_WAIT_V(8); PG8_WAIT_L(0); PG8_BAR; PG8_MMA(0, 0, At, B0); PG8_MMA(0, 1, At, B1); PG8_BAR; PG8_SCHED;
;     ...
;             PG8_LDA(At, 0, 1); PG8_STAGEB(PG8_SB(0, 0), b2, voffB); PG8_STAGEB(PG8_SB(0, 1), b2 + hstepB, voffB); PG8_STAGEA(PG8_SA(0, 0), a2, voffA);
;     ...
;             PG8_WAIT_VR(8, 24, relax); PG8_WAIT_L(0); PG8_BAR; PG8_MMA(1, 0, At, B0); PG8_MMA(1, 1, At, B1); PG8_BAR; PG8_SCHED;
;     ...
;             PG8_WAIT_V(8); PG8_WAIT_L(0); PG8_BAR; PG8_MMA(1, 0, At, B0); PG8_MMA(1, 1, At, B1); PG8_BAR; PG8_SCHED;
	v_mfma_f32_16x16x32_bf16 v[126:129], v[150:153], v[182:185], v[126:129]
	v_mfma_f32_16x16x32_bf16 v[122:125], v[158:161], v[182:185], v[122:125]
	v_mfma_f32_16x16x32_bf16 v[110:113], v[150:153], v[190:193], v[110:113]
	v_mfma_f32_16x16x32_bf16 v[106:109], v[158:161], v[190:193], v[106:109]
	v_mfma_f32_16x16x32_bf16 v[94:97], v[150:153], v[198:201], v[94:97]
	v_mfma_f32_16x16x32_bf16 v[90:93], v[158:161], v[198:201], v[90:93]
	v_mfma_f32_16x16x32_bf16 v[78:81], v[150:153], v[206:209], v[78:81]
	v_mfma_f32_16x16x32_bf16 v[74:77], v[158:161], v[206:209], v[74:77]
	v_mfma_f32_16x16x32_bf16 v[126:129], v[154:157], v[186:189], v[126:129]
	v_mfma_f32_16x16x32_bf16 v[122:125], v[162:165], v[186:189], v[122:125]
	v_mfma_f32_16x16x32_bf16 v[110:113], v[154:157], v[194:197], v[110:113]
	v_mfma_f32_16x16x32_bf16 v[106:109], v[162:165], v[194:197], v[106:109]
	v_mfma_f32_16x16x32_bf16 v[94:97], v[154:157], v[202:205], v[94:97]
	v_mfma_f32_16x16x32_bf16 v[90:93], v[162:165], v[202:205], v[90:93]
	v_mfma_f32_16x16x32_bf16 v[78:81], v[154:157], v[210:213], v[78:81]
	v_mfma_f32_16x16x32_bf16 v[74:77], v[162:165], v[210:213], v[74:77]
	v_mfma_f32_16x16x32_bf16 v[118:121], v[166:169], v[182:185], v[118:121]
	v_mfma_f32_16x16x32_bf16 v[114:117], v[174:177], v[182:185], v[114:117]
	v_mfma_f32_16x16x32_bf16 v[102:105], v[166:169], v[190:193], v[102:105]
	v_mfma_f32_16x16x32_bf16 v[98:101], v[174:177], v[190:193], v[98:101]
	v_mfma_f32_16x16x32_bf16 v[86:89], v[166:169], v[198:201], v[86:89]
	v_mfma_f32_16x16x32_bf16 v[82:85], v[174:177], v[198:201], v[82:85]
	v_mfma_f32_16x16x32_bf16 v[70:73], v[166:169], v[206:209], v[70:73]
	v_mfma_f32_16x16x32_bf16 v[66:69], v[174:177], v[206:209], v[66:69]
	v_mfma_f32_16x16x32_bf16 v[118:121], v[170:173], v[186:189], v[118:121]
	v_mfma_f32_16x16x32_bf16 v[114:117], v[178:181], v[186:189], v[114:117]
	v_mfma_f32_16x16x32_bf16 v[102:105], v[170:173], v[194:197], v[102:105]
	v_mfma_f32_16x16x32_bf16 v[98:101], v[178:181], v[194:197], v[98:101]
	v_mfma_f32_16x16x32_bf16 v[86:89], v[170:173], v[202:205], v[86:89]
	v_mfma_f32_16x16x32_bf16 v[82:85], v[178:181], v[202:205], v[82:85]
	v_mfma_f32_16x16x32_bf16 v[70:73], v[170:173], v[210:213], v[70:73]
	v_mfma_f32_16x16x32_bf16 v[66:69], v[178:181], v[210:213], v[66:69]
	s_barrier
	s_setprio 0
	s_add_i32 s6, s95, s50
	s_mov_b32 m0, s6
	ds_read_b128 v[182:185], v148 offset:16384
	ds_read_b128 v[186:189], v148 offset:17408
	ds_read_b128 v[190:193], v148 offset:18432
	ds_read_b128 v[194:197], v148 offset:19456
	ds_read_b128 v[198:201], v148 offset:20480
	ds_read_b128 v[202:205], v148 offset:21504
	ds_read_b128 v[206:209], v148 offset:22528
	ds_read_b128 v[210:213], v148 offset:23552
	global_load_lds_dwordx4 v134, s[16:17]
	s_add_i32 m0, s6, 0x2000
	s_add_u32 s6, s16, 0x100000
	s_addc_u32 s7, s17, 0
	s_add_i32 s95, vcc_lo, s50
	global_load_lds_dwordx4 v130, s[16:17]
	s_mov_b32 m0, s95
	s_nop 0
	global_load_lds_dwordx4 v134, s[6:7]
	s_add_i32 m0, s95, 0x2000
	s_nop 0
	global_load_lds_dwordx4 v130, s[6:7]
	s_mov_b32 m0, s69
	s_nop 0
	global_load_lds_dwordx4 v136, s[42:43]
	s_mov_b32 m0, s72
	s_nop 0
	global_load_lds_dwordx4 v132, s[42:43]
	s_waitcnt vmcnt(8)
	s_waitcnt lgkmcnt(0)
	s_setprio 1
	s_barrier
	v_mfma_f32_16x16x32_bf16 v[62:65], v[150:153], v[182:185], v[62:65]
	v_mfma_f32_16x16x32_bf16 v[58:61], v[158:161], v[182:185], v[58:61]
	v_mfma_f32_16x16x32_bf16 v[46:49], v[150:153], v[190:193], v[46:49]
	v_mfma_f32_16x16x32_bf16 v[42:45], v[158:161], v[190:193], v[42:45]
	v_mfma_f32_16x16x32_bf16 v[30:33], v[150:153], v[198:201], v[30:33]
	v_mfma_f32_16x16x32_bf16 v[26:29], v[158:161], v[198:201], v[26:29]
	v_mfma_f32_16x16x32_bf16 v[12:15], v[150:153], v[206:209], v[12:15]
	v_mfma_f32_16x16x32_bf16 v[8:11], v[158:161], v[206:209], v[8:11]
	v_mfma_f32_16x16x32_bf16 v[62:65], v[154:157], v[186:189], v[62:65]
	v_mfma_f32_16x16x32_bf16 v[58:61], v[162:165], v[186:189], v[58:61]
	v_mfma_f32_16x16x32_bf16 v[46:49], v[154:157], v[194:197], v[46:49]
	v_mfma_f32_16x16x32_bf16 v[42:45], v[162:165], v[194:197], v[42:45]
	v_mfma_f32_16x16x32_bf16 v[30:33], v[154:157], v[202:205], v[30:33]
	v_mfma_f32_16x16x32_bf16 v[26:29], v[162:165], v[202:205], v[26:29]
	v_mfma_f32_16x16x32_bf16 v[12:15], v[154:157], v[210:213], v[12:15]
	v_mfma_f32_16x16x32_bf16 v[8:11], v[162:165], v[210:213], v[8:11]
	v_mfma_f32_16x16x32_bf16 v[54:57], v[166:169], v[182:185], v[54:57]
	v_mfma_f32_16x16x32_bf16 v[50:53], v[174:177], v[182:185], v[50:53]
	v_mfma_f32_16x16x32_bf16 v[38:41], v[166:169], v[190:193], v[38:41]
	v_mfma_f32_16x16x32_bf16 v[34:37], v[174:177], v[190:193], v[34:37]
	v_mfma_f32_16x16x32_bf16 v[22:25], v[166:169], v[198:201], v[22:25]
	v_mfma_f32_16x16x32_bf16 v[18:21], v[174:177], v[198:201], v[18:21]
	v_mfma_f32_16x16x32_bf16 v[4:7], v[166:169], v[206:209], v[4:7]
	v_mfma_f32_16x16x32_bf16 v[0:3], v[174:177], v[206:209], v[0:3]
	v_mfma_f32_16x16x32_bf16 v[54:57], v[170:173], v[186:189], v[54:57]
	v_mfma_f32_16x16x32_bf16 v[50:53], v[178:181], v[186:189], v[50:53]
	v_mfma_f32_16x16x32_bf16 v[38:41], v[170:173], v[194:197], v[38:41]
	v_mfma_f32_16x16x32_bf16 v[34:37], v[178:181], v[194:197], v[34:37]
	v_mfma_f32_16x16x32_bf16 v[22:25], v[170:173], v[202:205], v[22:25]
	v_mfma_f32_16x16x32_bf16 v[18:21], v[178:181], v[202:205], v[18:21]
	v_mfma_f32_16x16x32_bf16 v[4:7], v[170:173], v[210:213], v[4:7]
	v_mfma_f32_16x16x32_bf16 v[0:3], v[178:181], v[210:213], v[0:3]
	s_barrier
; #define PG8_STAGEA(bufoff, gbase, voff) PG8_STAGE_X(bufoff, gbase, voff, AUXA)
; #define PG8_STAGEB(bufoff, gbase, voff) PG8_STAGE_X(bufoff, gbase, voff, AUXB)
; #define PG8_LDA(dst, b, h) do { _Pragma("unroll") for (int m = 0; m < 4; ++m) _Pragma("unroll") for (int k = 0; k < 2; ++k) dst[m][k] = *(const PG8_LAS bf16x8*)(lds + PG8_SA(b, h) + aoff + m * 2048 + k * 1024); } while (0)
; #define PG8_LDB(dst, b, h) do { _Pragma("unroll") for (int n = 0; n < 2; ++n) _Pragma("unroll") for (int k = 0; k < 2; ++k) dst[n][k] = *(const PG8_LAS bf16x8*)(lds + PG8_SB(b, h) + boff + n * 2048 + k * 1024); } while (0)
; #define PG8_MMA(ai, bj, At, Bt) do { if (GEMM_PRIO_MODE == 0) __builtin_amdgcn_s_setprio(1); PG8_MMA_LOOPS \
;         acc[ai][bj][m][n] = __builtin_amdgcn_mfma_f32_16x16x32_bf16(Bt[n][k], At[m][k], acc[ai][bj][m][n], 0, 0, 0); if (GEMM_PRIO_MODE == 0) __builtin_amdgcn_s_setprio(0); } while (0)
; #define PG8_WAIT_V(n) asm volatile("s_waitcnt vmcnt(" #n ")" ::: "memory")
; #define PG8_WAIT_L(n) asm volatile("s_waitcnt lgkmcnt(" #n ")" ::: "memory")
; #define PG8_BAR __builtin_amdgcn_s_barrier()
; #define PG8_SCHED __builtin_amdgcn_sched_barrier(0)
;     ...
;             PG8_LDB(B0, 1, 0); PG8_LDB(B1, 1, 1); PG8_SCHED; PG8_LDA(At, 1, 0); PG8_STAGEA(PG8_SA(0, 1), a2 + hstepA, voffA);
;             PG8_WAIT_V(8); PG8_WAIT_L(0); PG8_BAR; PG8_MMA(0, 0, At, B0); PG8_MMA(0, 1, At, B1); PG8_BAR; PG8_SCHED;
;             PG8_LDA(At, 1, 1); PG8_STAGEB(PG8_SB(1, 0), b3, voffB); PG8_STAGEB(PG8_SB(1, 1), b3 + hstepB, voffB); PG8_STAGEA(PG8_SA(1, 0), a3, voffA);
;             PG8_WAIT_V(8); PG8_WAIT_L(0); PG8_BAR; PG8_MMA(1, 0, At, B0); PG8_MMA(1, 1, At, B1); PG8_BAR; PG8_SCHED;
	s_setprio 0
	s_add_i32 s95, 0, 0x18000
	s_add_i32 vcc_lo, 0, 0x1c000
	ds_read_b128 v[150:153], v222 offset:32768
	ds_read_b128 v[154:157], v222 offset:33792
	ds_read_b128 v[158:161], v222 offset:34816
	ds_read_b128 v[162:165], v222 offset:35840
	ds_read_b128 v[166:169], v222 offset:49152
	ds_read_b128 v[170:173], v222 offset:50176
	ds_read_b128 v[174:177], v222 offset:51200
	ds_read_b128 v[178:181], v222 offset:52224
	s_add_u32 s6, s42, 0x100000
	s_addc_u32 s7, s43, 0
	s_mov_b32 m0, s73
	ds_read_b128 v[182:185], v148 offset:32768
	ds_read_b128 v[186:189], v148 offset:33792
	ds_read_b128 v[190:193], v148 offset:34816
	ds_read_b128 v[194:197], v148 offset:35840
	ds_read_b128 v[198:201], v148 offset:36864
	ds_read_b128 v[202:205], v148 offset:37888
	ds_read_b128 v[206:209], v148 offset:38912
	ds_read_b128 v[210:213], v148 offset:39936
	global_load_lds_dwordx4 v136, s[6:7]
	s_mov_b32 m0, s82
	s_nop 0
	global_load_lds_dwordx4 v132, s[6:7]
	s_waitcnt vmcnt(8)
	s_waitcnt lgkmcnt(0)
	s_setprio 1
	s_barrier
	v_mfma_f32_16x16x32_bf16 v[126:129], v[150:153], v[182:185], v[126:129]
	v_mfma_f32_16x16x32_bf16 v[122:125], v[158:161], v[182:185], v[122:125]
	v_mfma_f32_16x16x32_bf16 v[110:113], v[150:153], v[190:193], v[110:113]
	v_mfma_f32_16x16x32_bf16 v[106:109], v[158:161], v[190:193], v[106:109]
	v_mfma_f32_16x16x32_bf16 v[94:97], v[150:153], v[198:201], v[94:97]
	v_mfma_f32_16x16x32_bf16 v[90:93], v[158:161], v[198:201], v[90:93]
	v_mfma_f32_16x16x32_bf16 v[78:81], v[150:153], v[206:209], v[78:81]
	v_mfma_f32_16x16x32_bf16 v[74:77], v[158:161], v[206:209], v[74:77]
	v_mfma_f32_16x16x32_bf16 v[126:129], v[154:157], v[186:189], v[126:129]
	v_mfma_f32_16x16x32_bf16 v[122:125], v[162:165], v[186:189], v[122:125]
	v_mfma_f32_16x16x32_bf16 v[110:113], v[154:157], v[194:197], v[110:113]
	v_mfma_f32_16x16x32_bf16 v[106:109], v[162:165], v[194:197], v[106:109]
	v_mfma_f32_16x16x32_bf16 v[94:97], v[154:157], v[202:205], v[94:97]
	v_mfma_f32_16x16x32_bf16 v[90:93], v[162:165], v[202:205], v[90:93]
	v_mfma_f32_16x16x32_bf16 v[78:81], v[154:157], v[210:213], v[78:81]
	v_mfma_f32_16x16x32_bf16 v[74:77], v[162:165], v[210:213], v[74:77]
	v_mfma_f32_16x16x32_bf16 v[118:121], v[166:169], v[182:185], v[118:121]
	v_mfma_f32_16x16x32_bf16 v[114:117], v[174:177], v[182:185], v[114:117]
	v_mfma_f32_16x16x32_bf16 v[102:105], v[166:169], v[190:193], v[102:105]
	v_mfma_f32_16x16x32_bf16 v[98:101], v[174:177], v[190:193], v[98:101]
	v_mfma_f32_16x16x32_bf16 v[86:89], v[166:169], v[198:201], v[86:89]
	v_mfma_f32_16x16x32_bf16 v[82:85], v[174:177], v[198:201], v[82:85]
	v_mfma_f32_16x16x32_bf16 v[70:73], v[166:169], v[206:209], v[70:73]
	v_mfma_f32_16x16x32_bf16 v[66:69], v[174:177], v[206:209], v[66:69]
	v_mfma_f32_16x16x32_bf16 v[118:121], v[170:173], v[186:189], v[118:121]
	v_mfma_f32_16x16x32_bf16 v[114:117], v[178:181], v[186:189], v[114:117]
	v_mfma_f32_16x16x32_bf16 v[102:105], v[170:173], v[194:197], v[102:105]
	v_mfma_f32_16x16x32_bf16 v[98:101], v[178:181], v[194:197], v[98:101]
	v_mfma_f32_16x16x32_bf16 v[86:89], v[170:173], v[202:205], v[86:89]
	v_mfma_f32_16x16x32_bf16 v[82:85], v[178:181], v[202:205], v[82:85]
	v_mfma_f32_16x16x32_bf16 v[70:73], v[170:173], v[210:213], v[70:73]
	v_mfma_f32_16x16x32_bf16 v[66:69], v[178:181], v[210:213], v[66:69]
	s_barrier
	s_setprio 0
	s_add_i32 s6, s95, s50
	s_mov_b32 m0, s6
	ds_read_b128 v[182:185], v148 offset:49152
	ds_read_b128 v[186:189], v148 offset:50176
	ds_read_b128 v[190:193], v148 offset:51200
	ds_read_b128 v[194:197], v148 offset:52224
	ds_read_b128 v[198:201], v148 offset:53248
	ds_read_b128 v[202:205], v148 offset:54272
	ds_read_b128 v[206:209], v148 offset:55296
	ds_read_b128 v[210:213], v148 offset:56320
	s_add_u32 s100, s16, 0x80
	s_addc_u32 s101, s17, 0
	global_load_lds_dwordx4 v134, s[100:101]
	s_add_i32 m0, s6, 0x2000
	s_add_u32 s6, s16, 0x100080
	s_addc_u32 s7, s17, 0
	s_add_i32 s16, vcc_lo, s50
	global_load_lds_dwordx4 v130, s[100:101]
	s_mov_b32 m0, s16
	s_nop 0
	global_load_lds_dwordx4 v134, s[6:7]
	s_add_i32 m0, s16, 0x2000
	s_nop 0
	global_load_lds_dwordx4 v130, s[6:7]
	s_mov_b32 m0, s83
	s_nop 0
	s_add_u32 s100, s42, 0x80
	s_addc_u32 s101, s43, 0
	global_load_lds_dwordx4 v136, s[100:101]
	s_mov_b32 m0, s90
	s_nop 0
	global_load_lds_dwordx4 v132, s[100:101]
	s_waitcnt vmcnt(8)
	s_waitcnt lgkmcnt(0)
	s_setprio 1
	s_barrier
	v_mfma_f32_16x16x32_bf16 v[62:65], v[150:153], v[182:185], v[62:65]
	v_mfma_f32_16x16x32_bf16 v[58:61], v[158:161], v[182:185], v[58:61]
	v_mfma_f32_16x16x32_bf16 v[46:49], v[150:153], v[190:193], v[46:49]
	v_mfma_f32_16x16x32_bf16 v[42:45], v[158:161], v[190:193], v[42:45]
	v_mfma_f32_16x16x32_bf16 v[30:33], v[150:153], v[198:201], v[30:33]
	v_mfma_f32_16x16x32_bf16 v[26:29], v[158:161], v[198:201], v[26:29]
	v_mfma_f32_16x16x32_bf16 v[12:15], v[150:153], v[206:209], v[12:15]
	v_mfma_f32_16x16x32_bf16 v[8:11], v[158:161], v[206:209], v[8:11]
	v_mfma_f32_16x16x32_bf16 v[62:65], v[154:157], v[186:189], v[62:65]
	v_mfma_f32_16x16x32_bf16 v[58:61], v[162:165], v[186:189], v[58:61]
	v_mfma_f32_16x16x32_bf16 v[46:49], v[154:157], v[194:197], v[46:49]
	v_mfma_f32_16x16x32_bf16 v[42:45], v[162:165], v[194:197], v[42:45]
	v_mfma_f32_16x16x32_bf16 v[30:33], v[154:157], v[202:205], v[30:33]
	v_mfma_f32_16x16x32_bf16 v[26:29], v[162:165], v[202:205], v[26:29]
	v_mfma_f32_16x16x32_bf16 v[12:15], v[154:157], v[210:213], v[12:15]
	v_mfma_f32_16x16x32_bf16 v[8:11], v[162:165], v[210:213], v[8:11]
	v_mfma_f32_16x16x32_bf16 v[54:57], v[166:169], v[182:185], v[54:57]
	v_mfma_f32_16x16x32_bf16 v[50:53], v[174:177], v[182:185], v[50:53]
	v_mfma_f32_16x16x32_bf16 v[38:41], v[166:169], v[190:193], v[38:41]
	v_mfma_f32_16x16x32_bf16 v[34:37], v[174:177], v[190:193], v[34:37]
	v_mfma_f32_16x16x32_bf16 v[22:25], v[166:169], v[198:201], v[22:25]
	v_mfma_f32_16x16x32_bf16 v[18:21], v[174:177], v[198:201], v[18:21]
	v_mfma_f32_16x16x32_bf16 v[4:7], v[166:169], v[206:209], v[4:7]
	v_mfma_f32_16x16x32_bf16 v[0:3], v[174:177], v[206:209], v[0:3]
	v_mfma_f32_16x16x32_bf16 v[54:57], v[170:173], v[186:189], v[54:57]
	v_mfma_f32_16x16x32_bf16 v[50:53], v[178:181], v[186:189], v[50:53]
	v_mfma_f32_16x16x32_bf16 v[38:41], v[170:173], v[194:197], v[38:41]
	v_mfma_f32_16x16x32_bf16 v[34:37], v[178:181], v[194:197], v[34:37]
	v_mfma_f32_16x16x32_bf16 v[22:25], v[170:173], v[202:205], v[22:25]
	v_mfma_f32_16x16x32_bf16 v[18:21], v[178:181], v[202:205], v[18:21]
	v_mfma_f32_16x16x32_bf16 v[4:7], v[170:173], v[210:213], v[4:7]
	v_mfma_f32_16x16x32_bf16 v[0:3], v[178:181], v[210:213], v[0:3]
	s_barrier
	s_setprio 0
	s_add_i32 s39, s39, 2
	s_add_u32 s40, s40, 0x100
	s_addc_u32 s41, s41, 0
	s_add_u32 s12, s12, 0x100
	s_addc_u32 s13, s13, 0
	s_cmp_gt_u32 s39, 61
	s_cbranch_scc0 .LBB0_712
	s_and_b64 vcc, exec, s[18:19]
	s_cbranch_vccz .LBB0_715
	s_barrier

; #define PG8_STAGEA(bufoff, gbase, voff) PG8_STAGE_X(bufoff, gbase, voff, AUXA)
; #define PG8_LDA(dst, b, h) do { _Pragma("unroll") for (int m = 0; m < 4; ++m) _Pragma("unroll") for (int k = 0; k < 2; ++k) dst[m][k] = *(const PG8_LAS bf16x8*)(lds + PG8_SA(b, h) + aoff + m * 2048 + k * 1024); } while (0)
; #define PG8_LDB(dst, b, h) do { _Pragma("unroll") for (int n = 0; n < 2; ++n) _Pragma("unroll") for (int k = 0; k < 2; ++k) dst[n][k] = *(const PG8_LAS bf16x8*)(lds + PG8_SB(b, h) + boff + n * 2048 + k * 1024); } while (0)
; #define PG8_SCHED __builtin_amdgcn_sched_barrier(0)
;     ...
;         for (int t = t0; t < nt; t += 2) {
;             const bool last = (t == nt - 2);
;             const char* a1 = cA + (size_t)(t + 1) * kstepA;
;             const char* a2 = last ? nA : cA + (size_t)(t + 2) * kstepA; const char* b2 = last ? nB : cB + (size_t)(t + 2) * kstepB;
;             const char* a3 = a2 + kstepA; const char* b3 = b2 + kstepB;
;             if (last && has_next) S.a_ready(nxt);
;             if constexpr (SP2) {
;             PG8_LDB(B0, 0, 0); PG8_LDB(B1, 0, 1); PG8_SCHED; PG8_LDA(At, 0, 0); PG8_STAGEA(PG8_SA(1, 1), a1 + hstepA, voffA);
;     ...
; #pragma unroll
;         for (int a = 0; a < 2; ++a)
; #pragma unroll
;             for (int b = 0; b < 2; ++b)
; #pragma unroll
;                 for (int m = 0; m < 4; ++m)
; #pragma unroll
;                     for (int n = 0; n < 2; ++n) acc[a][b][m][n] = (f32x4){0.f, 0.f, 0.f, 0.f};
;         cur = nxt; cA = nA; cB = nB; ++ui;
.LBB0_847:
	s_ashr_i32 s11, s10, 31
	s_lshl_b64 s[18:19], s[10:11], 23
	s_add_u32 s18, s62, s18
	s_addc_u32 s19, s63, s19
	s_and_b64 s[22:23], s[20:21], exec
	s_cselect_b32 s11, s19, s1
	s_cselect_b32 s73, s18, s0
	s_ashr_i32 s15, s14, 31
	s_lshl_b64 s[22:23], s[14:15], 23
	s_add_u32 s22, s12, s22
	s_addc_u32 s23, s13, s23
	s_and_b64 s[24:25], s[20:21], exec
	s_cselect_b32 s15, s23, s17
	s_cselect_b32 s78, s22, s16
	s_add_u32 s24, s0, 0xc000
	s_addc_u32 s25, s1, 0
	s_add_u32 s0, s16, 0x10000
	v_mov_b32_e32 v0, 0
	s_addc_u32 s1, s17, 0
	s_mov_b32 s82, -2
	s_waitcnt lgkmcnt(0)
	v_mov_b32_e32 v1, v0
	v_mov_b32_e32 v2, v0
	v_mov_b32_e32 v3, v0
	v_mov_b32_e32 v4, v0
	v_mov_b32_e32 v5, v0
	v_mov_b32_e32 v6, v0
	v_mov_b32_e32 v7, v0
	v_mov_b32_e32 v18, v0
	v_mov_b32_e32 v19, v0
	v_mov_b32_e32 v20, v0
	v_mov_b32_e32 v21, v0
	v_mov_b32_e32 v22, v0
	v_mov_b32_e32 v23, v0
	v_mov_b32_e32 v24, v0
	v_mov_b32_e32 v25, v0
	v_mov_b32_e32 v34, v0
	v_mov_b32_e32 v35, v0
	v_mov_b32_e32 v36, v0
	v_mov_b32_e32 v37, v0
	v_mov_b32_e32 v38, v0
	v_mov_b32_e32 v39, v0
	v_mov_b32_e32 v40, v0
	v_mov_b32_e32 v41, v0
	v_mov_b32_e32 v50, v0
	v_mov_b32_e32 v51, v0
	v_mov_b32_e32 v52, v0
	v_mov_b32_e32 v53, v0
	v_mov_b32_e32 v54, v0
	v_mov_b32_e32 v55, v0
	v_mov_b32_e32 v56, v0
	v_mov_b32_e32 v57, v0
	v_mov_b32_e32 v8, v0
	v_mov_b32_e32 v9, v0
	v_mov_b32_e32 v10, v0
	v_mov_b32_e32 v11, v0
	v_mov_b32_e32 v12, v0
	v_mov_b32_e32 v13, v0
	v_mov_b32_e32 v14, v0
	v_mov_b32_e32 v15, v0
	v_mov_b32_e32 v26, v0
	v_mov_b32_e32 v27, v0
	v_mov_b32_e32 v28, v0
	v_mov_b32_e32 v29, v0
	v_mov_b32_e32 v30, v0
	v_mov_b32_e32 v31, v0
	v_mov_b32_e32 v32, v0
	v_mov_b32_e32 v33, v0
	v_mov_b32_e32 v42, v0
	v_mov_b32_e32 v43, v0
	v_mov_b32_e32 v44, v0
	v_mov_b32_e32 v45, v0
	v_mov_b32_e32 v46, v0
	v_mov_b32_e32 v47, v0
	v_mov_b32_e32 v48, v0
	v_mov_b32_e32 v49, v0
	v_mov_b32_e32 v58, v0
	v_mov_b32_e32 v59, v0
	v_mov_b32_e32 v60, v0
	v_mov_b32_e32 v61, v0
	v_mov_b32_e32 v62, v0
	v_mov_b32_e32 v63, v0
	v_mov_b32_e32 v64, v0
	v_mov_b32_e32 v65, v0
	v_mov_b32_e32 v66, v0
	v_mov_b32_e32 v67, v0
	v_mov_b32_e32 v68, v0
	v_mov_b32_e32 v69, v0
	v_mov_b32_e32 v70, v0
	v_mov_b32_e32 v71, v0
	v_mov_b32_e32 v72, v0
	v_mov_b32_e32 v73, v0
	v_mov_b32_e32 v82, v0
	v_mov_b32_e32 v83, v0
	v_mov_b32_e32 v84, v0
	v_mov_b32_e32 v85, v0
	v_mov_b32_e32 v86, v0
	v_mov_b32_e32 v87, v0
	v_mov_b32_e32 v88, v0
	v_mov_b32_e32 v89, v0
	v_mov_b32_e32 v98, v0
	v_mov_b32_e32 v99, v0
	v_mov_b32_e32 v100, v0
	v_mov_b32_e32 v101, v0
	v_mov_b32_e32 v102, v0
	v_mov_b32_e32 v103, v0
	v_mov_b32_e32 v104, v0
	v_mov_b32_e32 v105, v0
	v_mov_b32_e32 v114, v0
	v_mov_b32_e32 v115, v0
	v_mov_b32_e32 v116, v0
	v_mov_b32_e32 v117, v0
	v_mov_b32_e32 v118, v0
	v_mov_b32_e32 v119, v0
	v_mov_b32_e32 v120, v0
	v_mov_b32_e32 v121, v0
	v_mov_b32_e32 v74, v0
	v_mov_b32_e32 v75, v0
	v_mov_b32_e32 v76, v0
	v_mov_b32_e32 v77, v0
	v_mov_b32_e32 v78, v0
	v_mov_b32_e32 v79, v0
	v_mov_b32_e32 v80, v0
	v_mov_b32_e32 v81, v0
	v_mov_b32_e32 v90, v0
	v_mov_b32_e32 v91, v0
	v_mov_b32_e32 v92, v0
	v_mov_b32_e32 v93, v0
	v_mov_b32_e32 v94, v0
	v_mov_b32_e32 v95, v0
	v_mov_b32_e32 v96, v0
	v_mov_b32_e32 v97, v0
	v_mov_b32_e32 v106, v0
	v_mov_b32_e32 v107, v0
	v_mov_b32_e32 v108, v0
	v_mov_b32_e32 v109, v0
	v_mov_b32_e32 v110, v0
	v_mov_b32_e32 v111, v0
	v_mov_b32_e32 v112, v0
	v_mov_b32_e32 v113, v0
	v_mov_b32_e32 v122, v0
	v_mov_b32_e32 v123, v0
	v_mov_b32_e32 v124, v0
	v_mov_b32_e32 v125, v0
	v_mov_b32_e32 v126, v0
	v_mov_b32_e32 v127, v0
	v_mov_b32_e32 v128, v0
	v_mov_b32_e32 v129, v0
	v_add_u32_e32 v212, 0x10000, v157
.LBB0_848:
	s_add_u32 s16, s24, 0x4000
	s_addc_u32 s17, s25, 0
	s_cmpk_eq_i32 s82, 0xfc
	s_cselect_b32 s36, s73, s16
	s_cselect_b32 s37, s11, s17
	s_cselect_b32 s16, s78, s0
	s_cselect_b32 s17, s15, s1
	s_add_u32 s26, s36, 0x8000
	s_addc_u32 s27, s37, 0
	s_add_i32 s83, 0, 0x10000
	s_add_i32 s94, 0, 0x14000
	ds_read_b128 v[130:133], v212
	ds_read_b128 v[134:137], v212 offset:1024
	ds_read_b128 v[148:151], v212 offset:2048
	ds_read_b128 v[152:155], v212 offset:3072
	ds_read_b128 v[162:165], v212 offset:16384
	ds_read_b128 v[166:169], v212 offset:17408
	ds_read_b128 v[170:173], v212 offset:18432
	ds_read_b128 v[174:177], v212 offset:19456
	s_add_i32 m0, s39, 0xc000
	ds_read_b128 v[178:181], v161
	ds_read_b128 v[182:185], v161 offset:1024
	ds_read_b128 v[186:189], v161 offset:2048
	ds_read_b128 v[190:193], v161 offset:3072
	ds_read_b128 v[194:197], v161 offset:4096
	ds_read_b128 v[198:201], v161 offset:5120
	ds_read_b128 v[202:205], v161 offset:6144
	ds_read_b128 v[206:209], v161 offset:7168
	global_load_lds_dwordx4 v144, s[24:25]
	s_add_i32 m0, s39, 0xe000
	s_nop 0
	global_load_lds_dwordx4 v146, s[24:25]
	s_waitcnt vmcnt(8)
	s_waitcnt lgkmcnt(0)
	s_setprio 1
	s_barrier
; #define PG8_STAGEA(bufoff, gbase, voff) PG8_STAGE_X(bufoff, gbase, voff, AUXA)
; #define PG8_STAGEB(bufoff, gbase, voff) PG8_STAGE_X(bufoff, gbase, voff, AUXB)
; #define PG8_LDA(dst, b, h) do { _Pragma("unroll") for (int m = 0; m < 4; ++m) _Pragma("unroll") for (int k = 0; k < 2; ++k) dst[m][k] = *(const PG8_LAS bf16x8*)(lds + PG8_SA(b, h) + aoff + m * 2048 + k * 1024); } while (0)
; #define PG8_LDB(dst, b, h) do { _Pragma("unroll") for (int n = 0; n < 2; ++n) _Pragma("unroll") for (int k = 0; k < 2; ++k) dst[n][k] = *(const PG8_LAS bf16x8*)(lds + PG8_SB(b, h) + boff + n * 2048 + k * 1024); } while (0)
; #define PG8_MMA(ai, bj, At, Bt) do { if (GEMM_PRIO_MODE == 0) __builtin_amdgcn_s_setprio(1); PG8_MMA_LOOPS \
;         acc[ai][bj][m][n] = __builtin_amdgcn_mfma_f32_16x16x32_bf16(Bt[n][k], At[m][k], acc[ai][bj][m][n], 0, 0, 0); if (GEMM_PRIO_MODE == 0) __builtin_amdgcn_s_setprio(0); } while (0)
; #define PG8_WAIT_V(n) asm volatile("s_waitcnt vmcnt(" #n ")" ::: "memory")
; #define PG8_WAIT_VR(n, nr, flag) asm volatile("s_cmp_eq_u32 %0, 0\n\ts_cbranch_scc1 .Lpg8s%=\n\ts_waitcnt vmcnt(" #nr ")\n\ts_branch .Lpg8d%=\n.Lpg8s%=:\n\ts_waitcnt vmcnt(" #n ")\n.Lpg8d%=:" :: "s"(flag) : "memory", "scc")
; #define PG8_WAIT_L(n) asm volatile("s_waitcnt lgkmcnt(" #n ")" ::: "memory")
; #define PG8_BAR __builtin_amdgcn_s_barrier()
; #define PG8_SCHED __builtin_amdgcn_sched_barrier(0)
;     ...
;             PG8_LDB(B0, 0, 0); PG8_LDB(B1, 0, 1); PG8_SCHED; PG8_LDA(At, 0, 0); PG8_STAGEA(PG8_SA(1, 1), a1 + hstepA, voffA);
;     ...
;             const int relax = __builtin_amdgcn_readfirstlane((t == 0 && ui > 0) ? 1 : 0);
;             PG8_WAIT_VR(8, 24, relax); PG8_WAIT_L(0); PG8_BAR; PG8_MMA(0, 0, At, B0); PG8_MMA(0, 1, At, B1); PG8_BAR; PG8_SCHED;
;     ...
;             PG8_WAIT_V(8); PG8_WAIT_L(0); PG8_BAR; PG8_MMA(0, 0, At, B0); PG8_MMA(0, 1, At, B1); PG8_BAR; PG8_SCHED;
;     ...
;             PG8_LDA(At, 0, 1); PG8_STAGEB(PG8_SB(0, 0), b2, voffB); PG8_STAGEB(PG8_SB(0, 1), b2 + hstepB, voffB); PG8_STAGEA(PG8_SA(0, 0), a2, voffA);
;     ...
;             PG8_WAIT_VR(8, 24, relax); PG8_WAIT_L(0); PG8_BAR; PG8_MMA(1, 0, At, B0); PG8_MMA(1, 1, At, B1); PG8_BAR; PG8_SCHED;
;     ...
;             PG8_WAIT_V(8); PG8_WAIT_L(0); PG8_BAR; PG8_MMA(1, 0, At, B0); PG8_MMA(1, 1, At, B1); PG8_BAR; PG8_SCHED;
	v_mfma_f32_16x16x32_bf16 v[126:129], v[130:133], v[178:181], v[126:129]
	v_mfma_f32_16x16x32_bf16 v[122:125], v[148:151], v[178:181], v[122:125]
	v_mfma_f32_16x16x32_bf16 v[110:113], v[130:133], v[186:189], v[110:113]
	v_mfma_f32_16x16x32_bf16 v[106:109], v[148:151], v[186:189], v[106:109]
	v_mfma_f32_16x16x32_bf16 v[94:97], v[130:133], v[194:197], v[94:97]
	v_mfma_f32_16x16x32_bf16 v[90:93], v[148:151], v[194:197], v[90:93]
	v_mfma_f32_16x16x32_bf16 v[78:81], v[130:133], v[202:205], v[78:81]
	v_mfma_f32_16x16x32_bf16 v[74:77], v[148:151], v[202:205], v[74:77]
	v_mfma_f32_16x16x32_bf16 v[126:129], v[134:137], v[182:185], v[126:129]
	v_mfma_f32_16x16x32_bf16 v[122:125], v[152:155], v[182:185], v[122:125]
	v_mfma_f32_16x16x32_bf16 v[110:113], v[134:137], v[190:193], v[110:113]
	v_mfma_f32_16x16x32_bf16 v[106:109], v[152:155], v[190:193], v[106:109]
	v_mfma_f32_16x16x32_bf16 v[94:97], v[134:137], v[198:201], v[94:97]
	v_mfma_f32_16x16x32_bf16 v[90:93], v[152:155], v[198:201], v[90:93]
	v_mfma_f32_16x16x32_bf16 v[78:81], v[134:137], v[206:209], v[78:81]
	v_mfma_f32_16x16x32_bf16 v[74:77], v[152:155], v[206:209], v[74:77]
	v_mfma_f32_16x16x32_bf16 v[118:121], v[162:165], v[178:181], v[118:121]
	v_mfma_f32_16x16x32_bf16 v[114:117], v[170:173], v[178:181], v[114:117]
	v_mfma_f32_16x16x32_bf16 v[102:105], v[162:165], v[186:189], v[102:105]
	v_mfma_f32_16x16x32_bf16 v[98:101], v[170:173], v[186:189], v[98:101]
	v_mfma_f32_16x16x32_bf16 v[86:89], v[162:165], v[194:197], v[86:89]
	v_mfma_f32_16x16x32_bf16 v[82:85], v[170:173], v[194:197], v[82:85]
	v_mfma_f32_16x16x32_bf16 v[70:73], v[162:165], v[202:205], v[70:73]
	v_mfma_f32_16x16x32_bf16 v[66:69], v[170:173], v[202:205], v[66:69]
	v_mfma_f32_16x16x32_bf16 v[118:121], v[166:169], v[182:185], v[118:121]
	v_mfma_f32_16x16x32_bf16 v[114:117], v[174:177], v[182:185], v[114:117]
	v_mfma_f32_16x16x32_bf16 v[102:105], v[166:169], v[190:193], v[102:105]
	v_mfma_f32_16x16x32_bf16 v[98:101], v[174:177], v[190:193], v[98:101]
	v_mfma_f32_16x16x32_bf16 v[86:89], v[166:169], v[198:201], v[86:89]
	v_mfma_f32_16x16x32_bf16 v[82:85], v[174:177], v[198:201], v[82:85]
	v_mfma_f32_16x16x32_bf16 v[70:73], v[166:169], v[206:209], v[70:73]
	v_mfma_f32_16x16x32_bf16 v[66:69], v[174:177], v[206:209], v[66:69]
	s_barrier
	s_setprio 0
	s_add_i32 s83, s83, s38
	s_mov_b32 m0, s83
	ds_read_b128 v[178:181], v161 offset:16384
	ds_read_b128 v[182:185], v161 offset:17408
	ds_read_b128 v[186:189], v161 offset:18432
	ds_read_b128 v[190:193], v161 offset:19456
	ds_read_b128 v[194:197], v161 offset:20480
	ds_read_b128 v[198:201], v161 offset:21504
	ds_read_b128 v[202:205], v161 offset:22528
	ds_read_b128 v[206:209], v161 offset:23552
	global_load_lds_dwordx4 v16, s[16:17]
	s_add_i32 m0, s83, 0x2000
	s_add_u32 s90, s16, 0x4000
	s_addc_u32 s91, s17, 0
	s_add_i32 s83, s94, s38
	global_load_lds_dwordx4 v138, s[16:17]
	s_mov_b32 m0, s83
	s_nop 0
	global_load_lds_dwordx4 v16, s[90:91]
	s_add_i32 m0, s83, 0x2000
	s_nop 0
	global_load_lds_dwordx4 v138, s[90:91]
	s_mov_b32 m0, s39
	s_nop 0
	global_load_lds_dwordx4 v142, s[36:37]
	s_mov_b32 m0, s40
	s_nop 0
	global_load_lds_dwordx4 v140, s[36:37]
	s_waitcnt vmcnt(8)
	s_waitcnt lgkmcnt(0)
	s_setprio 1
	s_barrier
	v_mfma_f32_16x16x32_bf16 v[62:65], v[130:133], v[178:181], v[62:65]
	v_mfma_f32_16x16x32_bf16 v[58:61], v[148:151], v[178:181], v[58:61]
	v_mfma_f32_16x16x32_bf16 v[46:49], v[130:133], v[186:189], v[46:49]
	v_mfma_f32_16x16x32_bf16 v[42:45], v[148:151], v[186:189], v[42:45]
	v_mfma_f32_16x16x32_bf16 v[30:33], v[130:133], v[194:197], v[30:33]
	v_mfma_f32_16x16x32_bf16 v[26:29], v[148:151], v[194:197], v[26:29]
	v_mfma_f32_16x16x32_bf16 v[12:15], v[130:133], v[202:205], v[12:15]
	v_mfma_f32_16x16x32_bf16 v[8:11], v[148:151], v[202:205], v[8:11]
	v_mfma_f32_16x16x32_bf16 v[62:65], v[134:137], v[182:185], v[62:65]
	v_mfma_f32_16x16x32_bf16 v[58:61], v[152:155], v[182:185], v[58:61]
	v_mfma_f32_16x16x32_bf16 v[46:49], v[134:137], v[190:193], v[46:49]
	v_mfma_f32_16x16x32_bf16 v[42:45], v[152:155], v[190:193], v[42:45]
	v_mfma_f32_16x16x32_bf16 v[30:33], v[134:137], v[198:201], v[30:33]
	v_mfma_f32_16x16x32_bf16 v[26:29], v[152:155], v[198:201], v[26:29]
	v_mfma_f32_16x16x32_bf16 v[12:15], v[134:137], v[206:209], v[12:15]
	v_mfma_f32_16x16x32_bf16 v[8:11], v[152:155], v[206:209], v[8:11]
	v_mfma_f32_16x16x32_bf16 v[54:57], v[162:165], v[178:181], v[54:57]
	v_mfma_f32_16x16x32_bf16 v[50:53], v[170:173], v[178:181], v[50:53]
	v_mfma_f32_16x16x32_bf16 v[38:41], v[162:165], v[186:189], v[38:41]
	v_mfma_f32_16x16x32_bf16 v[34:37], v[170:173], v[186:189], v[34:37]
	v_mfma_f32_16x16x32_bf16 v[22:25], v[162:165], v[194:197], v[22:25]
	v_mfma_f32_16x16x32_bf16 v[18:21], v[170:173], v[194:197], v[18:21]
	v_mfma_f32_16x16x32_bf16 v[4:7], v[162:165], v[202:205], v[4:7]
	v_mfma_f32_16x16x32_bf16 v[0:3], v[170:173], v[202:205], v[0:3]
	v_mfma_f32_16x16x32_bf16 v[54:57], v[166:169], v[182:185], v[54:57]
	v_mfma_f32_16x16x32_bf16 v[50:53], v[174:177], v[182:185], v[50:53]
	v_mfma_f32_16x16x32_bf16 v[38:41], v[166:169], v[190:193], v[38:41]
	v_mfma_f32_16x16x32_bf16 v[34:37], v[174:177], v[190:193], v[34:37]
	v_mfma_f32_16x16x32_bf16 v[22:25], v[166:169], v[198:201], v[22:25]
	v_mfma_f32_16x16x32_bf16 v[18:21], v[174:177], v[198:201], v[18:21]
	v_mfma_f32_16x16x32_bf16 v[4:7], v[166:169], v[206:209], v[4:7]
	v_mfma_f32_16x16x32_bf16 v[0:3], v[174:177], v[206:209], v[0:3]
	s_barrier
; #define PG8_STAGEA(bufoff, gbase, voff) PG8_STAGE_X(bufoff, gbase, voff, AUXA)
; #define PG8_STAGEB(bufoff, gbase, voff) PG8_STAGE_X(bufoff, gbase, voff, AUXB)
; #define PG8_LDA(dst, b, h) do { _Pragma("unroll") for (int m = 0; m < 4; ++m) _Pragma("unroll") for (int k = 0; k < 2; ++k) dst[m][k] = *(const PG8_LAS bf16x8*)(lds + PG8_SA(b, h) + aoff + m * 2048 + k * 1024); } while (0)
; #define PG8_LDB(dst, b, h) do { _Pragma("unroll") for (int n = 0; n < 2; ++n) _Pragma("unroll") for (int k = 0; k < 2; ++k) dst[n][k] = *(const PG8_LAS bf16x8*)(lds + PG8_SB(b, h) + boff + n * 2048 + k * 1024); } while (0)
; #define PG8_MMA(ai, bj, At, Bt) do { if (GEMM_PRIO_MODE == 0) __builtin_amdgcn_s_setprio(1); PG8_MMA_LOOPS \
;         acc[ai][bj][m][n] = __builtin_amdgcn_mfma_f32_16x16x32_bf16(Bt[n][k], At[m][k], acc[ai][bj][m][n], 0, 0, 0); if (GEMM_PRIO_MODE == 0) __builtin_amdgcn_s_setprio(0); } while (0)
; #define PG8_WAIT_V(n) asm volatile("s_waitcnt vmcnt(" #n ")" ::: "memory")
; #define PG8_WAIT_L(n) asm volatile("s_waitcnt lgkmcnt(" #n ")" ::: "memory")
; #define PG8_BAR __builtin_amdgcn_s_barrier()
; #define PG8_SCHED __builtin_amdgcn_sched_barrier(0)
;     ...
;             PG8_LDB(B0, 1, 0); PG8_LDB(B1, 1, 1); PG8_SCHED; PG8_LDA(At, 1, 0); PG8_STAGEA(PG8_SA(0, 1), a2 + hstepA, voffA);
;             PG8_WAIT_V(8); PG8_WAIT_L(0); PG8_BAR; PG8_MMA(0, 0, At, B0); PG8_MMA(0, 1, At, B1); PG8_BAR; PG8_SCHED;
;             PG8_LDA(At, 1, 1); PG8_STAGEB(PG8_SB(1, 0), b3, voffB); PG8_STAGEB(PG8_SB(1, 1), b3 + hstepB, voffB); PG8_STAGEA(PG8_SA(1, 0), a3, voffA);
;             PG8_WAIT_V(8); PG8_WAIT_L(0); PG8_BAR; PG8_MMA(1, 0, At, B0); PG8_MMA(1, 1, At, B1); PG8_BAR; PG8_SCHED;
	s_setprio 0
	s_add_i32 s83, 0, 0x18000
	s_add_i32 s90, 0, 0x1c000
	ds_read_b128 v[130:133], v212 offset:32768
	ds_read_b128 v[134:137], v212 offset:33792
	ds_read_b128 v[148:151], v212 offset:34816
	ds_read_b128 v[152:155], v212 offset:35840
	ds_read_b128 v[162:165], v212 offset:49152
	ds_read_b128 v[166:169], v212 offset:50176
	ds_read_b128 v[170:173], v212 offset:51200
	ds_read_b128 v[174:177], v212 offset:52224
	s_add_u32 s36, s36, 0x4000
	s_addc_u32 s37, s37, 0
	s_mov_b32 m0, s41
	ds_read_b128 v[178:181], v161 offset:32768
	ds_read_b128 v[182:185], v161 offset:33792
	ds_read_b128 v[186:189], v161 offset:34816
	ds_read_b128 v[190:193], v161 offset:35840
	ds_read_b128 v[194:197], v161 offset:36864
	ds_read_b128 v[198:201], v161 offset:37888
	ds_read_b128 v[202:205], v161 offset:38912
	ds_read_b128 v[206:209], v161 offset:39936
	global_load_lds_dwordx4 v142, s[36:37]
	s_mov_b32 m0, s42
	s_nop 0
	global_load_lds_dwordx4 v140, s[36:37]
	s_waitcnt vmcnt(8)
	s_waitcnt lgkmcnt(0)
	s_setprio 1
	s_barrier
	v_mfma_f32_16x16x32_bf16 v[126:129], v[130:133], v[178:181], v[126:129]
	v_mfma_f32_16x16x32_bf16 v[122:125], v[148:151], v[178:181], v[122:125]
	v_mfma_f32_16x16x32_bf16 v[110:113], v[130:133], v[186:189], v[110:113]
	v_mfma_f32_16x16x32_bf16 v[106:109], v[148:151], v[186:189], v[106:109]
	v_mfma_f32_16x16x32_bf16 v[94:97], v[130:133], v[194:197], v[94:97]
	v_mfma_f32_16x16x32_bf16 v[90:93], v[148:151], v[194:197], v[90:93]
	v_mfma_f32_16x16x32_bf16 v[78:81], v[130:133], v[202:205], v[78:81]
	v_mfma_f32_16x16x32_bf16 v[74:77], v[148:151], v[202:205], v[74:77]
	v_mfma_f32_16x16x32_bf16 v[126:129], v[134:137], v[182:185], v[126:129]
	v_mfma_f32_16x16x32_bf16 v[122:125], v[152:155], v[182:185], v[122:125]
	v_mfma_f32_16x16x32_bf16 v[110:113], v[134:137], v[190:193], v[110:113]
	v_mfma_f32_16x16x32_bf16 v[106:109], v[152:155], v[190:193], v[106:109]
	v_mfma_f32_16x16x32_bf16 v[94:97], v[134:137], v[198:201], v[94:97]
	v_mfma_f32_16x16x32_bf16 v[90:93], v[152:155], v[198:201], v[90:93]
	v_mfma_f32_16x16x32_bf16 v[78:81], v[134:137], v[206:209], v[78:81]
	v_mfma_f32_16x16x32_bf16 v[74:77], v[152:155], v[206:209], v[74:77]
	v_mfma_f32_16x16x32_bf16 v[118:121], v[162:165], v[178:181], v[118:121]
	v_mfma_f32_16x16x32_bf16 v[114:117], v[170:173], v[178:181], v[114:117]
	v_mfma_f32_16x16x32_bf16 v[102:105], v[162:165], v[186:189], v[102:105]
	v_mfma_f32_16x16x32_bf16 v[98:101], v[170:173], v[186:189], v[98:101]
	v_mfma_f32_16x16x32_bf16 v[86:89], v[162:165], v[194:197], v[86:89]
	v_mfma_f32_16x16x32_bf16 v[82:85], v[170:173], v[194:197], v[82:85]
	v_mfma_f32_16x16x32_bf16 v[70:73], v[162:165], v[202:205], v[70:73]
	v_mfma_f32_16x16x32_bf16 v[66:69], v[170:173], v[202:205], v[66:69]
	v_mfma_f32_16x16x32_bf16 v[118:121], v[166:169], v[182:185], v[118:121]
	v_mfma_f32_16x16x32_bf16 v[114:117], v[174:177], v[182:185], v[114:117]
	v_mfma_f32_16x16x32_bf16 v[102:105], v[166:169], v[190:193], v[102:105]
	v_mfma_f32_16x16x32_bf16 v[98:101], v[174:177], v[190:193], v[98:101]
	v_mfma_f32_16x16x32_bf16 v[86:89], v[166:169], v[198:201], v[86:89]
	v_mfma_f32_16x16x32_bf16 v[82:85], v[174:177], v[198:201], v[82:85]
	v_mfma_f32_16x16x32_bf16 v[70:73], v[166:169], v[206:209], v[70:73]
	v_mfma_f32_16x16x32_bf16 v[66:69], v[174:177], v[206:209], v[66:69]
	s_barrier
	s_setprio 0
	s_add_u32 s36, s16, 0x8000
	s_addc_u32 s37, s17, 0
	s_add_i32 s83, s83, s38
	s_mov_b32 m0, s83
	ds_read_b128 v[178:181], v161 offset:49152
	ds_read_b128 v[182:185], v161 offset:50176
	ds_read_b128 v[186:189], v161 offset:51200
	ds_read_b128 v[190:193], v161 offset:52224
	ds_read_b128 v[194:197], v161 offset:53248
	ds_read_b128 v[198:201], v161 offset:54272
	ds_read_b128 v[202:205], v161 offset:55296
	ds_read_b128 v[206:209], v161 offset:56320
	global_load_lds_dwordx4 v16, s[36:37]
	s_add_i32 m0, s83, 0x2000
	s_add_u32 s16, s16, 0xc000
	s_addc_u32 s17, s17, 0
	global_load_lds_dwordx4 v138, s[36:37]
	s_add_i32 s36, s90, s38
	s_mov_b32 m0, s36
	s_nop 0
	global_load_lds_dwordx4 v16, s[16:17]
	s_add_i32 m0, s36, 0x2000
	s_nop 0
	global_load_lds_dwordx4 v138, s[16:17]
	s_mov_b32 m0, s50
	s_nop 0
	global_load_lds_dwordx4 v142, s[26:27]
	s_mov_b32 m0, s51
	s_nop 0
	global_load_lds_dwordx4 v140, s[26:27]
	s_waitcnt vmcnt(8)
	s_waitcnt lgkmcnt(0)
	s_setprio 1
	s_barrier
	v_mfma_f32_16x16x32_bf16 v[62:65], v[130:133], v[178:181], v[62:65]
	v_mfma_f32_16x16x32_bf16 v[58:61], v[148:151], v[178:181], v[58:61]
	v_mfma_f32_16x16x32_bf16 v[46:49], v[130:133], v[186:189], v[46:49]
	v_mfma_f32_16x16x32_bf16 v[42:45], v[148:151], v[186:189], v[42:45]
	v_mfma_f32_16x16x32_bf16 v[30:33], v[130:133], v[194:197], v[30:33]
	v_mfma_f32_16x16x32_bf16 v[26:29], v[148:151], v[194:197], v[26:29]
	v_mfma_f32_16x16x32_bf16 v[12:15], v[130:133], v[202:205], v[12:15]
	v_mfma_f32_16x16x32_bf16 v[8:11], v[148:151], v[202:205], v[8:11]
	v_mfma_f32_16x16x32_bf16 v[62:65], v[134:137], v[182:185], v[62:65]
	v_mfma_f32_16x16x32_bf16 v[58:61], v[152:155], v[182:185], v[58:61]
	v_mfma_f32_16x16x32_bf16 v[46:49], v[134:137], v[190:193], v[46:49]
	v_mfma_f32_16x16x32_bf16 v[42:45], v[152:155], v[190:193], v[42:45]
	v_mfma_f32_16x16x32_bf16 v[30:33], v[134:137], v[198:201], v[30:33]
	v_mfma_f32_16x16x32_bf16 v[26:29], v[152:155], v[198:201], v[26:29]
	v_mfma_f32_16x16x32_bf16 v[12:15], v[134:137], v[206:209], v[12:15]
	v_mfma_f32_16x16x32_bf16 v[8:11], v[152:155], v[206:209], v[8:11]
	v_mfma_f32_16x16x32_bf16 v[54:57], v[162:165], v[178:181], v[54:57]
	v_mfma_f32_16x16x32_bf16 v[50:53], v[170:173], v[178:181], v[50:53]
	v_mfma_f32_16x16x32_bf16 v[38:41], v[162:165], v[186:189], v[38:41]
	v_mfma_f32_16x16x32_bf16 v[34:37], v[170:173], v[186:189], v[34:37]
	v_mfma_f32_16x16x32_bf16 v[22:25], v[162:165], v[194:197], v[22:25]
	v_mfma_f32_16x16x32_bf16 v[18:21], v[170:173], v[194:197], v[18:21]
	v_mfma_f32_16x16x32_bf16 v[4:7], v[162:165], v[202:205], v[4:7]
	v_mfma_f32_16x16x32_bf16 v[0:3], v[170:173], v[202:205], v[0:3]
	v_mfma_f32_16x16x32_bf16 v[54:57], v[166:169], v[182:185], v[54:57]
	v_mfma_f32_16x16x32_bf16 v[50:53], v[174:177], v[182:185], v[50:53]
	v_mfma_f32_16x16x32_bf16 v[38:41], v[166:169], v[190:193], v[38:41]
	v_mfma_f32_16x16x32_bf16 v[34:37], v[174:177], v[190:193], v[34:37]
	v_mfma_f32_16x16x32_bf16 v[22:25], v[166:169], v[198:201], v[22:25]
	v_mfma_f32_16x16x32_bf16 v[18:21], v[174:177], v[198:201], v[18:21]
	v_mfma_f32_16x16x32_bf16 v[4:7], v[166:169], v[206:209], v[4:7]
	v_mfma_f32_16x16x32_bf16 v[0:3], v[174:177], v[206:209], v[0:3]
	s_barrier
	s_setprio 0
	s_add_i32 s82, s82, 2
	s_add_u32 s24, s24, 0x10000
	s_addc_u32 s25, s25, 0
	s_add_u32 s0, s0, 0x10000
	s_addc_u32 s1, s1, 0
	s_cmpk_gt_u32 s82, 0xfd
	s_cbranch_scc0 .LBB0_848
	s_and_b64 vcc, exec, s[8:9]
	s_cbranch_vccz .LBB0_851
	s_barrier

; __global__ void __launch_bounds__(NWAVES * 64, 2) hybrid_fwd(Args args) {
	.amdhsa_kernel _Z10hybrid_fwd4Args
		.amdhsa_group_segment_fixed_size 0
		.amdhsa_private_segment_fixed_size 0
		.amdhsa_kernarg_size 392
		.amdhsa_user_sgpr_count 2
		.amdhsa_user_sgpr_dispatch_ptr 0
		.amdhsa_user_sgpr_queue_ptr 0
		.amdhsa_user_sgpr_kernarg_segment_ptr 1
		.amdhsa_user_sgpr_dispatch_id 0
		.amdhsa_user_sgpr_kernarg_preload_length 0
		.amdhsa_user_sgpr_kernarg_preload_offset 0
		.amdhsa_user_sgpr_private_segment_size 0
		.amdhsa_uses_dynamic_stack 0
		.amdhsa_enable_private_segment 0
		.amdhsa_system_sgpr_workgroup_id_x 1
		.amdhsa_system_sgpr_workgroup_id_y 0
		.amdhsa_system_sgpr_workgroup_id_z 0
		.amdhsa_system_sgpr_workgroup_info 0
		.amdhsa_system_vgpr_workitem_id 0
		.amdhsa_next_free_vgpr 256
		.amdhsa_next_free_sgpr 102
		.amdhsa_accum_offset 256
		.amdhsa_reserve_vcc 1
		.amdhsa_float_round_mode_32 0
		.amdhsa_float_round_mode_16_64 0
		.amdhsa_float_denorm_mode_32 3
		.amdhsa_float_denorm_mode_16_64 3
		.amdhsa_dx10_clamp 1
		.amdhsa_ieee_mode 1
		.amdhsa_fp16_overflow 0
		.amdhsa_tg_split 0
		.amdhsa_exception_fp_ieee_invalid_op 0
		.amdhsa_exception_fp_denorm_src 0
		.amdhsa_exception_fp_ieee_div_zero 0
		.amdhsa_exception_fp_ieee_overflow 0
		.amdhsa_exception_fp_ieee_underflow 0
		.amdhsa_exception_fp_ieee_inexact 0
		.amdhsa_exception_int_div_zero 0
	.end_amdhsa_kernel

; __global__ void __launch_bounds__(NWAVES * 64, 2) hybrid_fwd(Args args) {
amdhsa.kernels:
  - .agpr_count:     0
    .args:
      - .offset:         0
        .size:           136
        .value_kind:     by_value
      - .offset:         136
        .size:           4
        .value_kind:     hidden_block_count_x
      - .offset:         140
        .size:           4
        .value_kind:     hidden_block_count_y
      - .offset:         144
        .size:           4
        .value_kind:     hidden_block_count_z
      - .offset:         148
        .size:           2
        .value_kind:     hidden_group_size_x
      - .offset:         150
        .size:           2
        .value_kind:     hidden_group_size_y
      - .offset:         152
        .size:           2
        .value_kind:     hidden_group_size_z
      - .offset:         154
        .size:           2
        .value_kind:     hidden_remainder_x
      - .offset:         156
        .size:           2
        .value_kind:     hidden_remainder_y
      - .offset:         158
        .size:           2
        .value_kind:     hidden_remainder_z
      - .offset:         176
        .size:           8
        .value_kind:     hidden_global_offset_x
      - .offset:         184
        .size:           8
        .value_kind:     hidden_global_offset_y
      - .offset:         192
        .size:           8
        .value_kind:     hidden_global_offset_z
      - .offset:         200
        .size:           2
        .value_kind:     hidden_grid_dims
      - .offset:         256
        .size:           4
        .value_kind:     hidden_dynamic_lds_size
    .group_segment_fixed_size: 0
    .kernarg_segment_align: 8
    .kernarg_segment_size: 392
    .language:       OpenCL C
    .language_version:
      - 2
      - 0
    .max_flat_workgroup_size: 512
    .name:           _Z10hybrid_fwd4Args
    .private_segment_fixed_size: 0
    .sgpr_count:     108
    .sgpr_spill_count: 166
    .symbol:         _Z10hybrid_fwd4Args.kd
    .uniform_work_group_size: 1
    .uses_dynamic_stack: false
    .vgpr_count:     256
    .vgpr_spill_count: 0
    .wavefront_size: 64
